# v26 + nt policy on the fused up-proj epilogue (HM) stores
# baseline (speedup 1.0000x reference)
;     __device__ __forceinline__ void operator()(f32x4 (&acc)[2][2][4][2], const Unit& u, int wr, int wc, int fr, int fq, PG8_LAS unsigned char* lds, int wid, int lane) const {
;     ...
;             for (int m = 0; m < 4; ++m) { const float rs = tbl[ai * HALF + wr * 64 + m * 16 + fr];
; #pragma unroll
;                 for (int bj = 0; bj < 2; ++bj)
; #pragma unroll
;                     for (int n = 0; n < 2; ++n) acc[ai][bj][m][n] = acc[ai][bj][m][n] * rs; }
;         if (fr >= 14) {
; #pragma unroll
;             for (int ai = 0; ai < 2; ++ai) { const int b = 2 * ai + wr; if (b < 3) {
; #pragma unroll
;                 for (int bj = 0; bj < 2; ++bj)
; #pragma unroll
;                     for (int n = 0; n < 2; ++n) *(PG8_LAS f32x4*)(X + (b * 2 + fr - 14) * 256 + bj * HALF + wc * 32 + 8 * fq + 4 * n) = acc[ai][bj][3][n]; } }
;         }
;         asm volatile("s_waitcnt lgkmcnt(0)" ::: "memory"); __builtin_amdgcn_s_barrier(); asm volatile("" ::: "memory");
;         unsigned pk0[2][4][2];
; #pragma unroll
;         for (int n = 0; n < 2; ++n) {
;             f32x4 w[2][3], bs[2];
; #pragma unroll
;             for (int bj = 0; bj < 2; ++bj) {
; #pragma unroll
;                 for (int k = 0; k < 3; ++k) w[bj][k] = *(const f32x4*)(cw + k * 11008 + bj * 5504 + j0 + 4 * n);
;                 bs[bj] = *(const f32x4*)(cb + bj * 5504 + j0 + 4 * n); }
; #pragma unroll
;             for (int ai = 0; ai < 2; ++ai) { const int b = 2 * ai + wr;
; #pragma unroll
;                 for (int m = 0; m < 4; ++m) { f32x4 c[2];
; #pragma unroll
;                     for (int bj = 0; bj < 2; ++bj) { const f32x4 cur = acc[ai][bj][m][n]; f32x4 prev;
;                         if (m > 0) prev = acc[ai][bj][m > 0 ? m - 1 : 0][n];
;                         else { prev = (f32x4){0.f, 0.f, 0.f, 0.f}; if (b > 0 && fr >= 14) prev = *(const PG8_LAS f32x4*)(X + ((b - 1) * 2 + fr - 14) * 256 + bj * HALF + wc * 32 + 8 * fq + 4 * n); }
;                         f32x4 p1, p2;
; #pragma unroll
;                         for (int j = 0; j < 4; ++j) { const float r1 = PG8_ROR(prev[j], 0x121), r2 = PG8_ROR(prev[j], 0x122);
;                             p1[j] = PG8_DPP(r1, cur[j], 0x111); p2[j] = PG8_DPP(r2, cur[j], 0x112); }
;                         c[bj] = bs[bj] + w[bj][0] * p2 + w[bj][1] * p1 + w[bj][2] * cur; }
;                     float h4[4];
; #pragma unroll
.LBB0_377:
	s_or_b64 exec, exec, s[0:1]
	s_lshl_b32 s0, s20, 7
	v_or_b32_e32 v112, s0, v232
	v_ashrrev_i32_e32 v113, 31, v112
	v_lshlrev_b64 v[112:113], 2, v[112:113]
	v_lshl_add_u64 v[202:203], s[16:17], 0, v[112:113]
	v_lshl_add_u64 v[200:201], s[22:23], 0, v[112:113]
	v_add_co_u32_e32 v112, vcc, 0xa000, v202
	s_waitcnt lgkmcnt(0)
	s_barrier
	s_nop 0
	v_addc_co_u32_e32 v113, vcc, 0, v203, vcc
	v_add_co_u32_e32 v114, vcc, 0x15000, v202
	global_load_dwordx4 v[126:129], v[202:203], off
	s_nop 0
	v_addc_co_u32_e32 v115, vcc, 0, v203, vcc
	global_load_dwordx4 v[134:137], v[112:113], off offset:3072
	global_load_dwordx4 v[130:133], v[114:115], off offset:2048
	global_load_dwordx4 v[142:145], v[200:201], off
	v_add_co_u32_e32 v112, vcc, 0x5000, v202
	s_mov_b32 s1, 0x10000
	s_nop 0
	v_addc_co_u32_e32 v113, vcc, 0, v203, vcc
	v_add_co_u32_e32 v204, vcc, s1, v202
	v_mov_b32_e32 v170, 0
	s_nop 0
	v_addc_co_u32_e32 v205, vcc, 0, v203, vcc
	global_load_dwordx4 v[114:117], v[112:113], off offset:1536
	global_load_dwordx4 v[118:121], v[204:205], off offset:512
	v_add_co_u32_e32 v112, vcc, 0x1a000, v202
	v_mov_b32_e32 v172, 0
	s_nop 0
	v_addc_co_u32_e32 v113, vcc, 0, v203, vcc
	global_load_dwordx4 v[122:125], v[112:113], off offset:3584
	v_add_co_u32_e32 v112, vcc, 0x5000, v200
	v_mov_b32_e32 v173, 0
	s_nop 0
	v_addc_co_u32_e32 v113, vcc, 0, v201, vcc
	global_load_dwordx4 v[138:141], v[112:113], off offset:1536
	v_mov_b32_e32 v174, 0
	v_mov_b32_e32 v175, 0
	s_and_saveexec_b64 s[86:87], s[78:79]
	ds_read_b128 v[172:175], v236
	s_or_b64 exec, exec, s[86:87]
	v_pk_mul_f32 v[160:161], v[160:161], v[198:199] op_sel_hi:[1,0]
	v_pk_mul_f32 v[158:159], v[158:159], v[198:199] op_sel_hi:[1,0]
	s_waitcnt lgkmcnt(0)
	v_mov_b32_dpp v112, v172 row_ror:1 row_mask:0xf bank_mask:0xf bound_ctrl:1
	v_mov_b32_dpp v206, v172 row_ror:2 row_mask:0xf bank_mask:0xf bound_ctrl:1
	v_mov_b32_dpp v113, v173 row_ror:1 row_mask:0xf bank_mask:0xf bound_ctrl:1
	v_mov_b32_dpp v207, v173 row_ror:2 row_mask:0xf bank_mask:0xf bound_ctrl:1
	v_mov_b32_dpp v208, v174 row_ror:1 row_mask:0xf bank_mask:0xf bound_ctrl:1
	v_mov_b32_dpp v174, v174 row_ror:2 row_mask:0xf bank_mask:0xf bound_ctrl:1
	v_mov_b32_dpp v209, v175 row_ror:1 row_mask:0xf bank_mask:0xf bound_ctrl:1
	v_mov_b32_dpp v175, v175 row_ror:2 row_mask:0xf bank_mask:0xf bound_ctrl:1
	v_mov_b32_dpp v112, v158 row_shr:1 row_mask:0xf bank_mask:0xf
	v_mov_b32_dpp v206, v158 row_shr:2 row_mask:0xf bank_mask:0xf
	v_mov_b32_dpp v113, v159 row_shr:1 row_mask:0xf bank_mask:0xf
	v_mov_b32_dpp v207, v159 row_shr:2 row_mask:0xf bank_mask:0xf
	v_mov_b32_dpp v208, v160 row_shr:1 row_mask:0xf bank_mask:0xf
	v_mov_b32_dpp v174, v160 row_shr:2 row_mask:0xf bank_mask:0xf
	v_mov_b32_dpp v209, v161 row_shr:1 row_mask:0xf bank_mask:0xf
	v_mov_b32_dpp v175, v161 row_shr:2 row_mask:0xf bank_mask:0xf
	v_mov_b32_e32 v171, 0
	v_mov_b32_e32 v172, 0
	v_mov_b32_e32 v173, 0
	s_and_saveexec_b64 s[86:87], s[78:79]
	ds_read_b128 v[170:173], v236 offset:512
	s_or_b64 exec, exec, s[86:87]
	s_waitcnt vmcnt(0)
	v_pk_fma_f32 v[174:175], v[128:129], v[174:175], v[144:145]
	v_pk_fma_f32 v[206:207], v[126:127], v[206:207], v[142:143]
	v_pk_fma_f32 v[174:175], v[136:137], v[208:209], v[174:175]
	v_pk_fma_f32 v[112:113], v[134:135], v[112:113], v[206:207]
	v_pk_fma_f32 v[206:207], v[160:161], v[132:133], v[174:175]
	v_mov_b32_e32 v199, v198
	v_mul_f32_e32 v0, 0xbfb8aa3b, v207
	v_exp_f32_e32 v0, v0
	v_mov_b32_e32 v174, v198
	v_mov_b32_e32 v175, v198
	v_pk_mul_f32 v[174:175], v[156:157], v[174:175]
	v_add_f32_e32 v0, 1.0, v0
	v_pk_mul_f32 v[208:209], v[154:155], v[198:199]
	v_pk_mul_f32 v[154:155], v[152:153], v[196:197] op_sel_hi:[1,0]
	v_pk_mul_f32 v[156:157], v[150:151], v[196:197] op_sel_hi:[1,0]
	v_pk_mul_f32 v[150:151], v[148:149], v[196:197] op_sel_hi:[1,0]
	v_pk_mul_f32 v[152:153], v[146:147], v[196:197] op_sel_hi:[1,0]
	v_pk_mul_f32 v[146:147], v[102:103], v[194:195] op_sel_hi:[1,0]
	v_pk_mul_f32 v[148:149], v[100:101], v[194:195] op_sel_hi:[1,0]
	v_pk_mul_f32 v[100:101], v[96:97], v[194:195] op_sel_hi:[1,0]
	s_waitcnt lgkmcnt(0)
	v_mov_b32_dpp v96, v170 row_ror:1 row_mask:0xf bank_mask:0xf bound_ctrl:1
	v_mov_b32_dpp v102, v170 row_ror:2 row_mask:0xf bank_mask:0xf bound_ctrl:1
	v_mov_b32_dpp v97, v171 row_ror:1 row_mask:0xf bank_mask:0xf bound_ctrl:1
	v_mov_b32_dpp v103, v171 row_ror:2 row_mask:0xf bank_mask:0xf bound_ctrl:1
	v_mov_b32_dpp v170, v172 row_ror:1 row_mask:0xf bank_mask:0xf bound_ctrl:1
	v_mov_b32_dpp v172, v172 row_ror:2 row_mask:0xf bank_mask:0xf bound_ctrl:1
	v_mov_b32_dpp v171, v173 row_ror:1 row_mask:0xf bank_mask:0xf bound_ctrl:1
	v_mov_b32_dpp v173, v173 row_ror:2 row_mask:0xf bank_mask:0xf bound_ctrl:1
	v_rcp_f32_e32 v0, v0
	v_mov_b32_dpp v172, v174 row_shr:2 row_mask:0xf bank_mask:0xf
	v_mov_b32_dpp v173, v175 row_shr:2 row_mask:0xf bank_mask:0xf
	v_mov_b32_dpp v102, v208 row_shr:2 row_mask:0xf bank_mask:0xf
	v_mov_b32_dpp v103, v209 row_shr:2 row_mask:0xf bank_mask:0xf
	v_mov_b32_dpp v170, v174 row_shr:1 row_mask:0xf bank_mask:0xf
	v_mov_b32_dpp v171, v175 row_shr:1 row_mask:0xf bank_mask:0xf
	v_pk_fma_f32 v[172:173], v[116:117], v[172:173], v[140:141]
	v_mov_b32_dpp v96, v208 row_shr:1 row_mask:0xf bank_mask:0xf
	v_mov_b32_dpp v97, v209 row_shr:1 row_mask:0xf bank_mask:0xf
	v_pk_fma_f32 v[102:103], v[114:115], v[102:103], v[138:139]
	v_pk_fma_f32 v[170:171], v[120:121], v[170:171], v[172:173]
	v_pk_fma_f32 v[96:97], v[118:119], v[96:97], v[102:103]
	v_pk_fma_f32 v[102:103], v[174:175], v[124:125], v[170:171]
	v_mul_f32_e32 v0, v207, v0
	v_mul_f32_e32 v0, v0, v103
	v_mul_f32_e32 v103, 0xbfb8aa3b, v206
	v_exp_f32_e32 v103, v103
; #define PG8_LAS __attribute__((address_space(3)))
; __device__ __forceinline__ unsigned cvt_pk_bf16(float lo, float hi) { unsigned r; asm volatile("v_cvt_pk_bf16_f32 %0, %1, %2" : "=v"(r) : "v"(lo), "v"(hi)); return r; }
; #define PG8_ROR(src, ctrl) __builtin_bit_cast(float, __builtin_amdgcn_mov_dpp(__builtin_bit_cast(int, (float)(src)), (ctrl), 0xf, 0xf, true))
; #define PG8_DPP(old, src, ctrl) __builtin_bit_cast(float, __builtin_amdgcn_update_dpp(__builtin_bit_cast(int, (float)(old)), __builtin_bit_cast(int, (float)(src)), (ctrl), 0xf, 0xf, false))
;     __device__ __forceinline__ void operator()(f32x4 (&acc)[2][2][4][2], const Unit& u, int wr, int wc, int fr, int fq, PG8_LAS unsigned char* lds, int wid, int lane) const {
;     ...
;                     for (int bj = 0; bj < 2; ++bj) { const f32x4 cur = acc[ai][bj][m][n]; f32x4 prev;
;                         if (m > 0) prev = acc[ai][bj][m > 0 ? m - 1 : 0][n];
;                         else { prev = (f32x4){0.f, 0.f, 0.f, 0.f}; if (b > 0 && fr >= 14) prev = *(const PG8_LAS f32x4*)(X + ((b - 1) * 2 + fr - 14) * 256 + bj * HALF + wc * 32 + 8 * fq + 4 * n); }
;                         f32x4 p1, p2;
; #pragma unroll
;                         for (int j = 0; j < 4; ++j) { const float r1 = PG8_ROR(prev[j], 0x121), r2 = PG8_ROR(prev[j], 0x122);
;                             p1[j] = PG8_DPP(r1, cur[j], 0x111); p2[j] = PG8_DPP(r2, cur[j], 0x112); }
;                         c[bj] = bs[bj] + w[bj][0] * p2 + w[bj][1] * p1 + w[bj][2] * cur; }
;                     float h4[4];
; #pragma unroll
;                     for (int j = 0; j < 4; ++j) h4[j] = c[0][j] * __builtin_amdgcn_rcpf(1.0f + __expf(-c[0][j])) * c[1][j];
;                     if (n == 0) { pk0[ai][m][0] = cvt_pk_bf16(h4[0], h4[1]); pk0[ai][m][1] = cvt_pk_bf16(h4[2], h4[3]); }
	v_pk_fma_f32 v[112:113], v[158:159], v[130:131], v[112:113]
	v_pk_fma_f32 v[96:97], v[208:209], v[122:123], v[96:97]
	v_mov_b32_dpp v172, v174 row_ror:2 row_mask:0xf bank_mask:0xf bound_ctrl:1
	v_add_f32_e32 v103, 1.0, v103
	v_rcp_f32_e32 v103, v103
	v_mov_b32_dpp v173, v175 row_ror:2 row_mask:0xf bank_mask:0xf bound_ctrl:1
	v_mov_b32_dpp v170, v174 row_ror:1 row_mask:0xf bank_mask:0xf bound_ctrl:1
	v_mov_b32_dpp v172, v150 row_shr:2 row_mask:0xf bank_mask:0xf
	v_mul_f32_e32 v103, v206, v103
	v_mul_f32_e32 v102, v103, v102
	v_mul_f32_e32 v103, 0xbfb8aa3b, v113
	v_exp_f32_e32 v103, v103
	v_mov_b32_dpp v171, v175 row_ror:1 row_mask:0xf bank_mask:0xf bound_ctrl:1
	v_mov_b32_dpp v173, v151 row_shr:2 row_mask:0xf bank_mask:0xf
	v_mov_b32_dpp v170, v150 row_shr:1 row_mask:0xf bank_mask:0xf
	v_add_f32_e32 v103, 1.0, v103
	v_rcp_f32_e32 v103, v103
	v_mov_b32_dpp v171, v151 row_shr:1 row_mask:0xf bank_mask:0xf
	v_pk_fma_f32 v[172:173], v[116:117], v[172:173], v[140:141]
	v_pk_mul_f32 v[98:99], v[98:99], v[194:195] op_sel_hi:[1,0]
	v_mul_f32_e32 v103, v113, v103
	v_mul_f32_e32 v97, v103, v97
	v_mul_f32_e32 v103, 0xbfb8aa3b, v112
	v_exp_f32_e32 v103, v103
	v_pk_fma_f32 v[170:171], v[120:121], v[170:171], v[172:173]
	v_add_f32_e32 v103, 1.0, v103
	v_rcp_f32_e32 v103, v103
	s_nop 0
	v_mul_f32_e32 v103, v112, v103
	v_mul_f32_e32 v96, v103, v96
	v_cvt_pk_bf16_f32 v112, v96, v97
	v_cvt_pk_bf16_f32 v113, v102, v0
	v_mov_b32_dpp v102, v158 row_ror:2 row_mask:0xf bank_mask:0xf bound_ctrl:1
	v_mov_b32_dpp v97, v159 row_ror:1 row_mask:0xf bank_mask:0xf bound_ctrl:1
	v_mov_b32_dpp v96, v158 row_ror:1 row_mask:0xf bank_mask:0xf bound_ctrl:1
	v_mov_b32_dpp v103, v159 row_ror:2 row_mask:0xf bank_mask:0xf bound_ctrl:1
	v_mov_b32_dpp v158, v160 row_ror:1 row_mask:0xf bank_mask:0xf bound_ctrl:1
	v_mov_b32_dpp v160, v160 row_ror:2 row_mask:0xf bank_mask:0xf bound_ctrl:1
	v_mov_b32_dpp v159, v161 row_ror:1 row_mask:0xf bank_mask:0xf bound_ctrl:1
	v_mov_b32_dpp v161, v161 row_ror:2 row_mask:0xf bank_mask:0xf bound_ctrl:1
	v_mov_b32_dpp v102, v156 row_shr:2 row_mask:0xf bank_mask:0xf
	v_mov_b32_dpp v103, v157 row_shr:2 row_mask:0xf bank_mask:0xf
	v_mov_b32_dpp v160, v154 row_shr:2 row_mask:0xf bank_mask:0xf
	v_mov_b32_dpp v161, v155 row_shr:2 row_mask:0xf bank_mask:0xf
	v_mov_b32_dpp v96, v156 row_shr:1 row_mask:0xf bank_mask:0xf
	v_mov_b32_dpp v97, v157 row_shr:1 row_mask:0xf bank_mask:0xf
	v_mov_b32_dpp v158, v154 row_shr:1 row_mask:0xf bank_mask:0xf
	v_mov_b32_dpp v159, v155 row_shr:1 row_mask:0xf bank_mask:0xf
	v_pk_fma_f32 v[160:161], v[128:129], v[160:161], v[144:145]
	v_pk_fma_f32 v[102:103], v[126:127], v[102:103], v[142:143]
	s_nop 0
	v_pk_fma_f32 v[96:97], v[134:135], v[96:97], v[102:103]
	v_pk_fma_f32 v[102:103], v[136:137], v[158:159], v[160:161]
	v_mov_b32_dpp v160, v208 row_ror:2 row_mask:0xf bank_mask:0xf bound_ctrl:1
	v_pk_fma_f32 v[102:103], v[154:155], v[132:133], v[102:103]
	v_mov_b32_dpp v161, v209 row_ror:2 row_mask:0xf bank_mask:0xf bound_ctrl:1
	v_mul_f32_e32 v0, 0xbfb8aa3b, v103
	v_exp_f32_e32 v0, v0
	v_mov_b32_dpp v158, v208 row_ror:1 row_mask:0xf bank_mask:0xf bound_ctrl:1
	v_mov_b32_dpp v160, v152 row_shr:2 row_mask:0xf bank_mask:0xf
	v_mov_b32_dpp v159, v209 row_ror:1 row_mask:0xf bank_mask:0xf bound_ctrl:1
	v_add_f32_e32 v0, 1.0, v0
	v_rcp_f32_e32 v0, v0
	v_mov_b32_dpp v161, v153 row_shr:2 row_mask:0xf bank_mask:0xf
	v_mov_b32_dpp v158, v152 row_shr:1 row_mask:0xf bank_mask:0xf
	v_mov_b32_dpp v159, v153 row_shr:1 row_mask:0xf bank_mask:0xf
	v_mul_f32_e32 v0, v103, v0
	v_mul_f32_e32 v103, 0xbfb8aa3b, v102
	v_exp_f32_e32 v103, v103
	v_pk_fma_f32 v[160:161], v[114:115], v[160:161], v[138:139]
	v_pk_fma_f32 v[96:97], v[156:157], v[130:131], v[96:97]
	v_pk_fma_f32 v[158:159], v[118:119], v[158:159], v[160:161]
	v_add_f32_e32 v103, 1.0, v103
	v_rcp_f32_e32 v103, v103
	v_pk_fma_f32 v[160:161], v[150:151], v[124:125], v[170:171]
	v_pk_fma_f32 v[158:159], v[152:153], v[122:123], v[158:159]
	v_mul_f32_e32 v0, v0, v161
	v_mul_f32_e32 v102, v102, v103
	v_mul_f32_e32 v103, v102, v160
	v_mul_f32_e32 v102, 0xbfb8aa3b, v97
	v_exp_f32_e32 v102, v102
	s_nop 0
	v_add_f32_e32 v102, 1.0, v102
	v_rcp_f32_e32 v102, v102
	s_nop 0
	v_mul_f32_e32 v97, v97, v102
	v_mul_f32_e32 v102, 0xbfb8aa3b, v96
	v_exp_f32_e32 v102, v102
	v_mul_f32_e32 v97, v97, v159
	v_mov_b32_dpp v159, v155 row_ror:1 row_mask:0xf bank_mask:0xf bound_ctrl:1
	v_mov_b32_dpp v155, v155 row_ror:2 row_mask:0xf bank_mask:0xf bound_ctrl:1
	v_add_f32_e32 v102, 1.0, v102
	v_rcp_f32_e32 v102, v102
	v_mov_b32_dpp v155, v147 row_shr:2 row_mask:0xf bank_mask:0xf
	v_mov_b32_dpp v159, v147 row_shr:1 row_mask:0xf bank_mask:0xf
	v_mul_f32_e32 v96, v96, v102
	v_mul_f32_e32 v96, v96, v158
	v_mov_b32_dpp v158, v154 row_ror:1 row_mask:0xf bank_mask:0xf bound_ctrl:1
	v_mov_b32_dpp v154, v154 row_ror:2 row_mask:0xf bank_mask:0xf bound_ctrl:1
	v_cvt_pk_bf16_f32 v102, v96, v97
	v_cvt_pk_bf16_f32 v103, v103, v0
	v_mov_b32_dpp v96, v156 row_ror:1 row_mask:0xf bank_mask:0xf bound_ctrl:1
	v_mov_b32_dpp v158, v146 row_shr:1 row_mask:0xf bank_mask:0xf
	v_mov_b32_dpp v154, v146 row_shr:2 row_mask:0xf bank_mask:0xf
	v_pk_fma_f32 v[154:155], v[128:129], v[154:155], v[144:145]
	v_mov_b32_dpp v156, v156 row_ror:2 row_mask:0xf bank_mask:0xf bound_ctrl:1
	v_pk_fma_f32 v[154:155], v[136:137], v[158:159], v[154:155]
	v_mov_b32_dpp v158, v150 row_ror:1 row_mask:0xf bank_mask:0xf bound_ctrl:1
	v_pk_fma_f32 v[154:155], v[146:147], v[132:133], v[154:155]
	v_mov_b32_dpp v150, v150 row_ror:2 row_mask:0xf bank_mask:0xf bound_ctrl:1
	v_mul_f32_e32 v0, 0xbfb8aa3b, v155
	v_exp_f32_e32 v0, v0
	v_mov_b32_dpp v159, v151 row_ror:1 row_mask:0xf bank_mask:0xf bound_ctrl:1
; #define PG8_LAS __attribute__((address_space(3)))
; __device__ __forceinline__ unsigned cvt_pk_bf16(float lo, float hi) { unsigned r; asm volatile("v_cvt_pk_bf16_f32 %0, %1, %2" : "=v"(r) : "v"(lo), "v"(hi)); return r; }
; #define PG8_ROR(src, ctrl) __builtin_bit_cast(float, __builtin_amdgcn_mov_dpp(__builtin_bit_cast(int, (float)(src)), (ctrl), 0xf, 0xf, true))
; #define PG8_DPP(old, src, ctrl) __builtin_bit_cast(float, __builtin_amdgcn_update_dpp(__builtin_bit_cast(int, (float)(old)), __builtin_bit_cast(int, (float)(src)), (ctrl), 0xf, 0xf, false))
;     __device__ __forceinline__ void operator()(f32x4 (&acc)[2][2][4][2], const Unit& u, int wr, int wc, int fr, int fq, PG8_LAS unsigned char* lds, int wid, int lane) const {
;     ...
;             for (int ai = 0; ai < 2; ++ai) { const int b = 2 * ai + wr;
; #pragma unroll
;                 for (int m = 0; m < 4; ++m) { f32x4 c[2];
; #pragma unroll
;                     for (int bj = 0; bj < 2; ++bj) { const f32x4 cur = acc[ai][bj][m][n]; f32x4 prev;
;                         if (m > 0) prev = acc[ai][bj][m > 0 ? m - 1 : 0][n];
;                         else { prev = (f32x4){0.f, 0.f, 0.f, 0.f}; if (b > 0 && fr >= 14) prev = *(const PG8_LAS f32x4*)(X + ((b - 1) * 2 + fr - 14) * 256 + bj * HALF + wc * 32 + 8 * fq + 4 * n); }
;                         f32x4 p1, p2;
; #pragma unroll
;                         for (int j = 0; j < 4; ++j) { const float r1 = PG8_ROR(prev[j], 0x121), r2 = PG8_ROR(prev[j], 0x122);
;                             p1[j] = PG8_DPP(r1, cur[j], 0x111); p2[j] = PG8_DPP(r2, cur[j], 0x112); }
;                         c[bj] = bs[bj] + w[bj][0] * p2 + w[bj][1] * p1 + w[bj][2] * cur; }
;                     float h4[4];
; #pragma unroll
;                     for (int j = 0; j < 4; ++j) h4[j] = c[0][j] * __builtin_amdgcn_rcpf(1.0f + __expf(-c[0][j])) * c[1][j];
;                     if (n == 0) { pk0[ai][m][0] = cvt_pk_bf16(h4[0], h4[1]); pk0[ai][m][1] = cvt_pk_bf16(h4[2], h4[3]); }
	v_mov_b32_dpp v151, v151 row_ror:2 row_mask:0xf bank_mask:0xf bound_ctrl:1
	v_mov_b32_dpp v150, v98 row_shr:2 row_mask:0xf bank_mask:0xf
	v_add_f32_e32 v0, 1.0, v0
	v_rcp_f32_e32 v0, v0
	v_mov_b32_dpp v151, v99 row_shr:2 row_mask:0xf bank_mask:0xf
	v_mov_b32_dpp v158, v98 row_shr:1 row_mask:0xf bank_mask:0xf
	v_mov_b32_dpp v159, v99 row_shr:1 row_mask:0xf bank_mask:0xf
	v_pk_fma_f32 v[150:151], v[116:117], v[150:151], v[140:141]
	v_mul_f32_e32 v0, v155, v0
	v_pk_fma_f32 v[150:151], v[120:121], v[158:159], v[150:151]
	v_mov_b32_dpp v97, v157 row_ror:1 row_mask:0xf bank_mask:0xf bound_ctrl:1
	v_pk_fma_f32 v[150:151], v[98:99], v[124:125], v[150:151]
	v_mov_b32_dpp v157, v157 row_ror:2 row_mask:0xf bank_mask:0xf bound_ctrl:1
	v_mul_f32_e32 v0, v0, v151
	v_mul_f32_e32 v151, 0xbfb8aa3b, v154
	v_exp_f32_e32 v151, v151
	v_mov_b32_dpp v156, v148 row_shr:2 row_mask:0xf bank_mask:0xf
	v_mov_b32_dpp v157, v149 row_shr:2 row_mask:0xf bank_mask:0xf
	v_mov_b32_dpp v96, v148 row_shr:1 row_mask:0xf bank_mask:0xf
	v_add_f32_e32 v151, 1.0, v151
	v_rcp_f32_e32 v151, v151
	v_mov_b32_dpp v97, v149 row_shr:1 row_mask:0xf bank_mask:0xf
	v_pk_fma_f32 v[156:157], v[126:127], v[156:157], v[142:143]
	v_mul_f32_e32 v151, v154, v151
	v_pk_fma_f32 v[96:97], v[134:135], v[96:97], v[156:157]
	v_mul_f32_e32 v150, v151, v150
	v_pk_fma_f32 v[96:97], v[148:149], v[130:131], v[96:97]
	v_mov_b32_dpp v156, v152 row_ror:1 row_mask:0xf bank_mask:0xf bound_ctrl:1
	v_mul_f32_e32 v151, 0xbfb8aa3b, v97
	v_exp_f32_e32 v151, v151
	v_mov_b32_dpp v152, v152 row_ror:2 row_mask:0xf bank_mask:0xf bound_ctrl:1
	v_mov_b32_dpp v157, v153 row_ror:1 row_mask:0xf bank_mask:0xf bound_ctrl:1
	v_mov_b32_dpp v153, v153 row_ror:2 row_mask:0xf bank_mask:0xf bound_ctrl:1
	v_add_f32_e32 v151, 1.0, v151
	v_rcp_f32_e32 v151, v151
	v_mov_b32_dpp v152, v100 row_shr:2 row_mask:0xf bank_mask:0xf
	v_mov_b32_dpp v153, v101 row_shr:2 row_mask:0xf bank_mask:0xf
	v_mov_b32_dpp v156, v100 row_shr:1 row_mask:0xf bank_mask:0xf
	v_mul_f32_e32 v97, v97, v151
	v_mul_f32_e32 v151, 0xbfb8aa3b, v96
	v_exp_f32_e32 v151, v151
	v_mov_b32_dpp v157, v101 row_shr:1 row_mask:0xf bank_mask:0xf
	v_pk_fma_f32 v[152:153], v[114:115], v[152:153], v[138:139]
	v_add_f32_e32 v151, 1.0, v151
	v_rcp_f32_e32 v151, v151
	v_pk_fma_f32 v[152:153], v[118:119], v[156:157], v[152:153]
	v_mul_f32_e32 v96, v96, v151
	v_pk_fma_f32 v[152:153], v[100:101], v[122:123], v[152:153]
	v_mov_b32_dpp v151, v149 row_ror:1 row_mask:0xf bank_mask:0xf bound_ctrl:1
	v_mul_f32_e32 v97, v97, v153
	v_mul_f32_e32 v96, v96, v152
	v_mov_b32_dpp v152, v146 row_ror:1 row_mask:0xf bank_mask:0xf bound_ctrl:1
	v_mov_b32_dpp v146, v146 row_ror:2 row_mask:0xf bank_mask:0xf bound_ctrl:1
	v_mov_b32_dpp v153, v147 row_ror:1 row_mask:0xf bank_mask:0xf bound_ctrl:1
	v_mov_b32_dpp v147, v147 row_ror:2 row_mask:0xf bank_mask:0xf bound_ctrl:1
	v_mov_b32_dpp v146, v168 row_shr:2 row_mask:0xf bank_mask:0xf
	v_mov_b32_dpp v152, v168 row_shr:1 row_mask:0xf bank_mask:0xf
	v_mov_b32_dpp v147, v169 row_shr:2 row_mask:0xf bank_mask:0xf
	v_mov_b32_dpp v153, v169 row_shr:1 row_mask:0xf bank_mask:0xf
	v_pk_fma_f32 v[146:147], v[128:129], v[146:147], v[144:145]
	v_cvt_pk_bf16_f32 v96, v96, v97
	v_cvt_pk_bf16_f32 v97, v150, v0
	v_mov_b32_dpp v150, v148 row_ror:1 row_mask:0xf bank_mask:0xf bound_ctrl:1
	v_pk_fma_f32 v[146:147], v[136:137], v[152:153], v[146:147]
	v_mov_b32_dpp v152, v98 row_ror:1 row_mask:0xf bank_mask:0xf bound_ctrl:1
	v_pk_fma_f32 v[146:147], v[168:169], v[132:133], v[146:147]
	v_mov_b32_dpp v98, v98 row_ror:2 row_mask:0xf bank_mask:0xf bound_ctrl:1
	v_mul_f32_e32 v0, 0xbfb8aa3b, v147
	v_exp_f32_e32 v0, v0
	v_mov_b32_dpp v153, v99 row_ror:1 row_mask:0xf bank_mask:0xf bound_ctrl:1
	v_mov_b32_dpp v99, v99 row_ror:2 row_mask:0xf bank_mask:0xf bound_ctrl:1
	v_mov_b32_dpp v98, v164 row_shr:2 row_mask:0xf bank_mask:0xf
	v_add_f32_e32 v0, 1.0, v0
	v_rcp_f32_e32 v0, v0
	v_mov_b32_dpp v99, v165 row_shr:2 row_mask:0xf bank_mask:0xf
	v_mov_b32_dpp v152, v164 row_shr:1 row_mask:0xf bank_mask:0xf
	v_mov_b32_dpp v153, v165 row_shr:1 row_mask:0xf bank_mask:0xf
	v_pk_fma_f32 v[98:99], v[116:117], v[98:99], v[140:141]
	v_mul_f32_e32 v0, v147, v0
	v_pk_fma_f32 v[98:99], v[120:121], v[152:153], v[98:99]
	v_mov_b32_dpp v148, v148 row_ror:2 row_mask:0xf bank_mask:0xf bound_ctrl:1
	v_pk_fma_f32 v[98:99], v[164:165], v[124:125], v[98:99]
	v_mov_b32_dpp v149, v149 row_ror:2 row_mask:0xf bank_mask:0xf bound_ctrl:1
	v_mul_f32_e32 v0, v0, v99
	v_mul_f32_e32 v99, 0xbfb8aa3b, v146
	v_exp_f32_e32 v99, v99
	v_mov_b32_dpp v148, v166 row_shr:2 row_mask:0xf bank_mask:0xf
	v_mov_b32_dpp v149, v167 row_shr:2 row_mask:0xf bank_mask:0xf
	v_mov_b32_dpp v150, v166 row_shr:1 row_mask:0xf bank_mask:0xf
	v_add_f32_e32 v99, 1.0, v99
	v_rcp_f32_e32 v99, v99
	v_mov_b32_dpp v151, v167 row_shr:1 row_mask:0xf bank_mask:0xf
	v_pk_fma_f32 v[148:149], v[126:127], v[148:149], v[142:143]
	v_mul_f32_e32 v99, v146, v99
	v_pk_fma_f32 v[148:149], v[134:135], v[150:151], v[148:149]
	v_mul_f32_e32 v98, v99, v98
	v_pk_fma_f32 v[148:149], v[166:167], v[130:131], v[148:149]
	v_mov_b32_dpp v150, v100 row_ror:1 row_mask:0xf bank_mask:0xf bound_ctrl:1
	v_mul_f32_e32 v99, 0xbfb8aa3b, v149
	v_exp_f32_e32 v99, v99
	v_mov_b32_dpp v100, v100 row_ror:2 row_mask:0xf bank_mask:0xf bound_ctrl:1
	v_mov_b32_dpp v151, v101 row_ror:1 row_mask:0xf bank_mask:0xf bound_ctrl:1
	v_mov_b32_dpp v101, v101 row_ror:2 row_mask:0xf bank_mask:0xf bound_ctrl:1
	v_add_f32_e32 v99, 1.0, v99
	v_rcp_f32_e32 v99, v99
	v_mov_b32_dpp v100, v162 row_shr:2 row_mask:0xf bank_mask:0xf
	v_mov_b32_dpp v101, v163 row_shr:2 row_mask:0xf bank_mask:0xf
	v_mov_b32_dpp v150, v162 row_shr:1 row_mask:0xf bank_mask:0xf
	v_mov_b32_dpp v151, v163 row_shr:1 row_mask:0xf bank_mask:0xf
	v_pk_fma_f32 v[100:101], v[114:115], v[100:101], v[138:139]
	v_mul_f32_e32 v99, v149, v99
	v_pk_fma_f32 v[100:101], v[118:119], v[150:151], v[100:101]
	v_mov_b32_e32 v146, 0
	v_pk_fma_f32 v[100:101], v[162:163], v[122:123], v[100:101]
	v_mov_b32_e32 v149, 0
	v_mul_f32_e32 v99, v99, v101
	v_mul_f32_e32 v101, 0xbfb8aa3b, v148
	v_exp_f32_e32 v101, v101
	v_mov_b32_e32 v150, 0
	v_mov_b32_e32 v151, 0
	v_add_f32_e32 v101, 1.0, v101
	v_rcp_f32_e32 v101, v101
	s_nop 0
	v_mul_f32_e32 v101, v148, v101
	v_mul_f32_e32 v100, v101, v100
	v_mov_b32_e32 v148, 0
	v_cvt_pk_bf16_f32 v100, v100, v99
	v_cvt_pk_bf16_f32 v101, v98, v0
	s_and_saveexec_b64 s[86:87], s[80:81]
	ds_read_b128 v[148:151], v237
	s_or_b64 exec, exec, s[86:87]
	v_pk_mul_f32 v[94:95], v[94:95], v[192:193] op_sel_hi:[1,0]
	v_pk_mul_f32 v[98:99], v[92:93], v[192:193] op_sel_hi:[1,0]
	s_waitcnt lgkmcnt(0)
; #define PG8_LAS __attribute__((address_space(3)))
; __device__ __forceinline__ unsigned cvt_pk_bf16(float lo, float hi) { unsigned r; asm volatile("v_cvt_pk_bf16_f32 %0, %1, %2" : "=v"(r) : "v"(lo), "v"(hi)); return r; }
; #define PG8_ROR(src, ctrl) __builtin_bit_cast(float, __builtin_amdgcn_mov_dpp(__builtin_bit_cast(int, (float)(src)), (ctrl), 0xf, 0xf, true))
; #define PG8_DPP(old, src, ctrl) __builtin_bit_cast(float, __builtin_amdgcn_update_dpp(__builtin_bit_cast(int, (float)(old)), __builtin_bit_cast(int, (float)(src)), (ctrl), 0xf, 0xf, false))
;     __device__ __forceinline__ void operator()(f32x4 (&acc)[2][2][4][2], const Unit& u, int wr, int wc, int fr, int fq, PG8_LAS unsigned char* lds, int wid, int lane) const {
;     ...
;             for (int ai = 0; ai < 2; ++ai) { const int b = 2 * ai + wr;
; #pragma unroll
;                 for (int m = 0; m < 4; ++m) { f32x4 c[2];
; #pragma unroll
;                     for (int bj = 0; bj < 2; ++bj) { const f32x4 cur = acc[ai][bj][m][n]; f32x4 prev;
;                         if (m > 0) prev = acc[ai][bj][m > 0 ? m - 1 : 0][n];
;                         else { prev = (f32x4){0.f, 0.f, 0.f, 0.f}; if (b > 0 && fr >= 14) prev = *(const PG8_LAS f32x4*)(X + ((b - 1) * 2 + fr - 14) * 256 + bj * HALF + wc * 32 + 8 * fq + 4 * n); }
;                         f32x4 p1, p2;
; #pragma unroll
;                         for (int j = 0; j < 4; ++j) { const float r1 = PG8_ROR(prev[j], 0x121), r2 = PG8_ROR(prev[j], 0x122);
;                             p1[j] = PG8_DPP(r1, cur[j], 0x111); p2[j] = PG8_DPP(r2, cur[j], 0x112); }
;                         c[bj] = bs[bj] + w[bj][0] * p2 + w[bj][1] * p1 + w[bj][2] * cur; }
;                     float h4[4];
; #pragma unroll
;                     for (int j = 0; j < 4; ++j) h4[j] = c[0][j] * __builtin_amdgcn_rcpf(1.0f + __expf(-c[0][j])) * c[1][j];
;                     if (n == 0) { pk0[ai][m][0] = cvt_pk_bf16(h4[0], h4[1]); pk0[ai][m][1] = cvt_pk_bf16(h4[2], h4[3]); }
	v_mov_b32_dpp v92, v148 row_ror:1 row_mask:0xf bank_mask:0xf bound_ctrl:1
	v_mov_b32_dpp v152, v148 row_ror:2 row_mask:0xf bank_mask:0xf bound_ctrl:1
	v_mov_b32_dpp v93, v149 row_ror:1 row_mask:0xf bank_mask:0xf bound_ctrl:1
	v_mov_b32_dpp v153, v149 row_ror:2 row_mask:0xf bank_mask:0xf bound_ctrl:1
	v_mov_b32_dpp v154, v150 row_ror:1 row_mask:0xf bank_mask:0xf bound_ctrl:1
	v_mov_b32_dpp v150, v150 row_ror:2 row_mask:0xf bank_mask:0xf bound_ctrl:1
	v_mov_b32_dpp v155, v151 row_ror:1 row_mask:0xf bank_mask:0xf bound_ctrl:1
	v_mov_b32_dpp v151, v151 row_ror:2 row_mask:0xf bank_mask:0xf bound_ctrl:1
	v_mov_b32_dpp v92, v98 row_shr:1 row_mask:0xf bank_mask:0xf
	v_mov_b32_dpp v152, v98 row_shr:2 row_mask:0xf bank_mask:0xf
	v_mov_b32_dpp v93, v99 row_shr:1 row_mask:0xf bank_mask:0xf
	v_mov_b32_dpp v153, v99 row_shr:2 row_mask:0xf bank_mask:0xf
	v_mov_b32_dpp v154, v94 row_shr:1 row_mask:0xf bank_mask:0xf
	v_mov_b32_dpp v150, v94 row_shr:2 row_mask:0xf bank_mask:0xf
	v_mov_b32_dpp v155, v95 row_shr:1 row_mask:0xf bank_mask:0xf
	v_mov_b32_dpp v151, v95 row_shr:2 row_mask:0xf bank_mask:0xf
	v_mov_b32_e32 v147, 0
	v_mov_b32_e32 v148, 0
	v_mov_b32_e32 v149, 0
	s_and_saveexec_b64 s[86:87], s[80:81]
	ds_read_b128 v[146:149], v237 offset:512
	s_or_b64 exec, exec, s[86:87]
	v_pk_fma_f32 v[150:151], v[128:129], v[150:151], v[144:145]
	v_pk_fma_f32 v[152:153], v[126:127], v[152:153], v[142:143]
	v_pk_fma_f32 v[150:151], v[136:137], v[154:155], v[150:151]
	v_pk_fma_f32 v[92:93], v[134:135], v[92:93], v[152:153]
	v_pk_fma_f32 v[152:153], v[94:95], v[132:133], v[150:151]
	v_pk_fma_f32 v[154:155], v[98:99], v[130:131], v[92:93]
	v_mul_f32_e32 v0, 0xbfb8aa3b, v153
	v_exp_f32_e32 v0, v0
	v_mov_b32_e32 v92, v192
	v_mov_b32_e32 v93, v192
	v_mov_b32_e32 v193, v192
	v_add_f32_e32 v0, 1.0, v0
	v_pk_mul_f32 v[150:151], v[90:91], v[92:93]
	v_pk_mul_f32 v[90:91], v[86:87], v[190:191] op_sel_hi:[1,0]
	v_pk_mul_f32 v[92:93], v[84:85], v[190:191] op_sel_hi:[1,0]
	v_pk_mul_f32 v[86:87], v[82:83], v[190:191] op_sel_hi:[1,0]
	v_pk_mul_f32 v[82:83], v[78:79], v[188:189] op_sel_hi:[1,0]
	v_pk_mul_f32 v[84:85], v[76:77], v[188:189] op_sel_hi:[1,0]
	v_pk_mul_f32 v[76:77], v[72:73], v[188:189] op_sel_hi:[1,0]
	s_waitcnt lgkmcnt(0)
	v_mov_b32_dpp v72, v146 row_ror:1 row_mask:0xf bank_mask:0xf bound_ctrl:1
	v_mov_b32_dpp v78, v146 row_ror:2 row_mask:0xf bank_mask:0xf bound_ctrl:1
	v_mov_b32_dpp v73, v147 row_ror:1 row_mask:0xf bank_mask:0xf bound_ctrl:1
	v_mov_b32_dpp v79, v147 row_ror:2 row_mask:0xf bank_mask:0xf bound_ctrl:1
	v_mov_b32_dpp v146, v148 row_ror:2 row_mask:0xf bank_mask:0xf bound_ctrl:1
	v_mov_b32_dpp v147, v149 row_ror:2 row_mask:0xf bank_mask:0xf bound_ctrl:1
	v_rcp_f32_e32 v0, v0
	v_pk_mul_f32 v[156:157], v[88:89], v[192:193]
	v_pk_mul_f32 v[88:89], v[80:81], v[190:191] op_sel_hi:[1,0]
	v_mov_b32_dpp v80, v148 row_ror:1 row_mask:0xf bank_mask:0xf bound_ctrl:1
	v_mov_b32_dpp v146, v150 row_shr:2 row_mask:0xf bank_mask:0xf
	v_mov_b32_dpp v81, v149 row_ror:1 row_mask:0xf bank_mask:0xf bound_ctrl:1
	v_mov_b32_dpp v147, v151 row_shr:2 row_mask:0xf bank_mask:0xf
	v_mov_b32_dpp v78, v156 row_shr:2 row_mask:0xf bank_mask:0xf
	v_mov_b32_dpp v79, v157 row_shr:2 row_mask:0xf bank_mask:0xf
	v_mov_b32_dpp v80, v150 row_shr:1 row_mask:0xf bank_mask:0xf
	v_mov_b32_dpp v81, v151 row_shr:1 row_mask:0xf bank_mask:0xf
	v_pk_fma_f32 v[146:147], v[116:117], v[146:147], v[140:141]
	v_mov_b32_dpp v72, v156 row_shr:1 row_mask:0xf bank_mask:0xf
	v_mov_b32_dpp v73, v157 row_shr:1 row_mask:0xf bank_mask:0xf
	v_pk_fma_f32 v[78:79], v[114:115], v[78:79], v[138:139]
	v_pk_fma_f32 v[80:81], v[120:121], v[80:81], v[146:147]
	v_pk_fma_f32 v[72:73], v[118:119], v[72:73], v[78:79]
	v_pk_fma_f32 v[78:79], v[150:151], v[124:125], v[80:81]
	v_mul_f32_e32 v0, v153, v0
	v_mul_f32_e32 v0, v0, v79
	v_mul_f32_e32 v79, 0xbfb8aa3b, v152
	v_exp_f32_e32 v79, v79
	v_pk_fma_f32 v[72:73], v[156:157], v[122:123], v[72:73]
	v_mov_b32_dpp v148, v150 row_ror:2 row_mask:0xf bank_mask:0xf bound_ctrl:1
	v_mov_b32_dpp v149, v151 row_ror:2 row_mask:0xf bank_mask:0xf bound_ctrl:1
	v_add_f32_e32 v79, 1.0, v79
	v_rcp_f32_e32 v79, v79
	v_mov_b32_dpp v146, v150 row_ror:1 row_mask:0xf bank_mask:0xf bound_ctrl:1
	v_mov_b32_dpp v148, v86 row_shr:2 row_mask:0xf bank_mask:0xf
	v_mov_b32_dpp v147, v151 row_ror:1 row_mask:0xf bank_mask:0xf bound_ctrl:1
	v_mul_f32_e32 v79, v152, v79
	v_mul_f32_e32 v78, v79, v78
	v_mul_f32_e32 v79, 0xbfb8aa3b, v155
	v_exp_f32_e32 v79, v79
	v_mov_b32_dpp v149, v87 row_shr:2 row_mask:0xf bank_mask:0xf
	v_mov_b32_dpp v146, v86 row_shr:1 row_mask:0xf bank_mask:0xf
	v_mov_b32_dpp v147, v87 row_shr:1 row_mask:0xf bank_mask:0xf
	v_add_f32_e32 v79, 1.0, v79
	v_rcp_f32_e32 v79, v79
	v_pk_fma_f32 v[148:149], v[116:117], v[148:149], v[140:141]
	v_pk_mul_f32 v[74:75], v[74:75], v[188:189] op_sel_hi:[1,0]
	v_pk_fma_f32 v[146:147], v[120:121], v[146:147], v[148:149]
	v_mul_f32_e32 v79, v155, v79
	v_mul_f32_e32 v73, v79, v73
	v_mul_f32_e32 v79, 0xbfb8aa3b, v154
	v_exp_f32_e32 v79, v79
	s_mov_b32 s1, 0xa000
	v_add_f32_e32 v79, 1.0, v79
	v_rcp_f32_e32 v79, v79
	s_nop 0
	v_mul_f32_e32 v79, v154, v79
	v_mul_f32_e32 v72, v79, v72
	v_cvt_pk_bf16_f32 v80, v72, v73
	v_cvt_pk_bf16_f32 v81, v78, v0
	v_mov_b32_dpp v78, v98 row_ror:2 row_mask:0xf bank_mask:0xf bound_ctrl:1
	v_mov_b32_dpp v73, v99 row_ror:1 row_mask:0xf bank_mask:0xf bound_ctrl:1
	v_mov_b32_dpp v72, v98 row_ror:1 row_mask:0xf bank_mask:0xf bound_ctrl:1
	v_mov_b32_dpp v79, v99 row_ror:2 row_mask:0xf bank_mask:0xf bound_ctrl:1
	v_mov_b32_dpp v98, v94 row_ror:1 row_mask:0xf bank_mask:0xf bound_ctrl:1
	v_mov_b32_dpp v94, v94 row_ror:2 row_mask:0xf bank_mask:0xf bound_ctrl:1
; #define PG8_LAS __attribute__((address_space(3)))
; __device__ __forceinline__ unsigned cvt_pk_bf16(float lo, float hi) { unsigned r; asm volatile("v_cvt_pk_bf16_f32 %0, %1, %2" : "=v"(r) : "v"(lo), "v"(hi)); return r; }
; #define PG8_ROR(src, ctrl) __builtin_bit_cast(float, __builtin_amdgcn_mov_dpp(__builtin_bit_cast(int, (float)(src)), (ctrl), 0xf, 0xf, true))
; #define PG8_DPP(old, src, ctrl) __builtin_bit_cast(float, __builtin_amdgcn_update_dpp(__builtin_bit_cast(int, (float)(old)), __builtin_bit_cast(int, (float)(src)), (ctrl), 0xf, 0xf, false))
;     __device__ __forceinline__ void operator()(f32x4 (&acc)[2][2][4][2], const Unit& u, int wr, int wc, int fr, int fq, PG8_LAS unsigned char* lds, int wid, int lane) const {
;     ...
;                     for (int bj = 0; bj < 2; ++bj) { const f32x4 cur = acc[ai][bj][m][n]; f32x4 prev;
;                         if (m > 0) prev = acc[ai][bj][m > 0 ? m - 1 : 0][n];
;                         else { prev = (f32x4){0.f, 0.f, 0.f, 0.f}; if (b > 0 && fr >= 14) prev = *(const PG8_LAS f32x4*)(X + ((b - 1) * 2 + fr - 14) * 256 + bj * HALF + wc * 32 + 8 * fq + 4 * n); }
;                         f32x4 p1, p2;
; #pragma unroll
;                         for (int j = 0; j < 4; ++j) { const float r1 = PG8_ROR(prev[j], 0x121), r2 = PG8_ROR(prev[j], 0x122);
;                             p1[j] = PG8_DPP(r1, cur[j], 0x111); p2[j] = PG8_DPP(r2, cur[j], 0x112); }
;                         c[bj] = bs[bj] + w[bj][0] * p2 + w[bj][1] * p1 + w[bj][2] * cur; }
;                     float h4[4];
; #pragma unroll
;                     for (int j = 0; j < 4; ++j) h4[j] = c[0][j] * __builtin_amdgcn_rcpf(1.0f + __expf(-c[0][j])) * c[1][j];
;                     if (n == 0) { pk0[ai][m][0] = cvt_pk_bf16(h4[0], h4[1]); pk0[ai][m][1] = cvt_pk_bf16(h4[2], h4[3]); }
	v_mov_b32_dpp v99, v95 row_ror:1 row_mask:0xf bank_mask:0xf bound_ctrl:1
	v_mov_b32_dpp v95, v95 row_ror:2 row_mask:0xf bank_mask:0xf bound_ctrl:1
	v_mov_b32_dpp v78, v92 row_shr:2 row_mask:0xf bank_mask:0xf
	v_mov_b32_dpp v79, v93 row_shr:2 row_mask:0xf bank_mask:0xf
	v_mov_b32_dpp v94, v90 row_shr:2 row_mask:0xf bank_mask:0xf
	v_mov_b32_dpp v95, v91 row_shr:2 row_mask:0xf bank_mask:0xf
	v_mov_b32_dpp v72, v92 row_shr:1 row_mask:0xf bank_mask:0xf
	v_mov_b32_dpp v73, v93 row_shr:1 row_mask:0xf bank_mask:0xf
	v_mov_b32_dpp v98, v90 row_shr:1 row_mask:0xf bank_mask:0xf
	v_mov_b32_dpp v99, v91 row_shr:1 row_mask:0xf bank_mask:0xf
	v_pk_fma_f32 v[94:95], v[128:129], v[94:95], v[144:145]
	v_pk_fma_f32 v[78:79], v[126:127], v[78:79], v[142:143]
	s_nop 0
	v_pk_fma_f32 v[72:73], v[134:135], v[72:73], v[78:79]
	v_pk_fma_f32 v[78:79], v[136:137], v[98:99], v[94:95]
	v_mov_b32_dpp v98, v156 row_ror:2 row_mask:0xf bank_mask:0xf bound_ctrl:1
	v_pk_fma_f32 v[78:79], v[90:91], v[132:133], v[78:79]
	v_mov_b32_dpp v99, v157 row_ror:2 row_mask:0xf bank_mask:0xf bound_ctrl:1
	v_mul_f32_e32 v0, 0xbfb8aa3b, v79
	v_exp_f32_e32 v0, v0
	v_mov_b32_dpp v94, v156 row_ror:1 row_mask:0xf bank_mask:0xf bound_ctrl:1
	v_mov_b32_dpp v98, v88 row_shr:2 row_mask:0xf bank_mask:0xf
	v_mov_b32_dpp v95, v157 row_ror:1 row_mask:0xf bank_mask:0xf bound_ctrl:1
	v_add_f32_e32 v0, 1.0, v0
	v_rcp_f32_e32 v0, v0
	v_mov_b32_dpp v99, v89 row_shr:2 row_mask:0xf bank_mask:0xf
	v_mov_b32_dpp v94, v88 row_shr:1 row_mask:0xf bank_mask:0xf
	v_mov_b32_dpp v95, v89 row_shr:1 row_mask:0xf bank_mask:0xf
	v_mul_f32_e32 v0, v79, v0
	v_mul_f32_e32 v79, 0xbfb8aa3b, v78
	v_exp_f32_e32 v79, v79
	v_pk_fma_f32 v[98:99], v[114:115], v[98:99], v[138:139]
	v_pk_fma_f32 v[72:73], v[92:93], v[130:131], v[72:73]
	v_pk_fma_f32 v[94:95], v[118:119], v[94:95], v[98:99]
	v_add_f32_e32 v79, 1.0, v79
	v_rcp_f32_e32 v79, v79
	v_pk_fma_f32 v[98:99], v[86:87], v[124:125], v[146:147]
	v_pk_fma_f32 v[94:95], v[88:89], v[122:123], v[94:95]
	v_mul_f32_e32 v0, v0, v99
	v_mul_f32_e32 v78, v78, v79
	v_mul_f32_e32 v79, v78, v98
	v_mul_f32_e32 v78, 0xbfb8aa3b, v73
	v_exp_f32_e32 v78, v78
	s_nop 0
	v_add_f32_e32 v78, 1.0, v78
	v_rcp_f32_e32 v78, v78
	s_nop 0
	v_mul_f32_e32 v73, v73, v78
	v_mul_f32_e32 v78, 0xbfb8aa3b, v72
	v_exp_f32_e32 v78, v78
	v_mul_f32_e32 v73, v73, v95
	v_mov_b32_dpp v95, v91 row_ror:1 row_mask:0xf bank_mask:0xf bound_ctrl:1
	v_mov_b32_dpp v91, v91 row_ror:2 row_mask:0xf bank_mask:0xf bound_ctrl:1
	v_add_f32_e32 v78, 1.0, v78
	v_rcp_f32_e32 v78, v78
	v_mov_b32_dpp v91, v83 row_shr:2 row_mask:0xf bank_mask:0xf
	v_mov_b32_dpp v95, v83 row_shr:1 row_mask:0xf bank_mask:0xf
	v_mul_f32_e32 v72, v72, v78
	v_mul_f32_e32 v72, v72, v94
	v_mov_b32_dpp v94, v90 row_ror:1 row_mask:0xf bank_mask:0xf bound_ctrl:1
	v_mov_b32_dpp v90, v90 row_ror:2 row_mask:0xf bank_mask:0xf bound_ctrl:1
	v_cvt_pk_bf16_f32 v78, v72, v73
	v_cvt_pk_bf16_f32 v79, v79, v0
	v_mov_b32_dpp v72, v92 row_ror:1 row_mask:0xf bank_mask:0xf bound_ctrl:1
	v_mov_b32_dpp v94, v82 row_shr:1 row_mask:0xf bank_mask:0xf
	v_mov_b32_dpp v90, v82 row_shr:2 row_mask:0xf bank_mask:0xf
	v_pk_fma_f32 v[90:91], v[128:129], v[90:91], v[144:145]
	v_mov_b32_dpp v92, v92 row_ror:2 row_mask:0xf bank_mask:0xf bound_ctrl:1
	v_pk_fma_f32 v[90:91], v[136:137], v[94:95], v[90:91]
	v_mov_b32_dpp v94, v86 row_ror:1 row_mask:0xf bank_mask:0xf bound_ctrl:1
	v_pk_fma_f32 v[90:91], v[82:83], v[132:133], v[90:91]
	v_mov_b32_dpp v86, v86 row_ror:2 row_mask:0xf bank_mask:0xf bound_ctrl:1
	v_mul_f32_e32 v0, 0xbfb8aa3b, v91
	v_exp_f32_e32 v0, v0
	v_mov_b32_dpp v95, v87 row_ror:1 row_mask:0xf bank_mask:0xf bound_ctrl:1
	v_mov_b32_dpp v87, v87 row_ror:2 row_mask:0xf bank_mask:0xf bound_ctrl:1
	v_mov_b32_dpp v86, v74 row_shr:2 row_mask:0xf bank_mask:0xf
	v_add_f32_e32 v0, 1.0, v0
	v_rcp_f32_e32 v0, v0
	v_mov_b32_dpp v87, v75 row_shr:2 row_mask:0xf bank_mask:0xf
	v_mov_b32_dpp v94, v74 row_shr:1 row_mask:0xf bank_mask:0xf
	v_mov_b32_dpp v95, v75 row_shr:1 row_mask:0xf bank_mask:0xf
	v_pk_fma_f32 v[86:87], v[116:117], v[86:87], v[140:141]
	v_mul_f32_e32 v0, v91, v0
	v_pk_fma_f32 v[86:87], v[120:121], v[94:95], v[86:87]
	v_mov_b32_dpp v73, v93 row_ror:1 row_mask:0xf bank_mask:0xf bound_ctrl:1
	v_pk_fma_f32 v[86:87], v[74:75], v[124:125], v[86:87]
	v_mov_b32_dpp v93, v93 row_ror:2 row_mask:0xf bank_mask:0xf bound_ctrl:1
	v_mul_f32_e32 v0, v0, v87
	v_mul_f32_e32 v87, 0xbfb8aa3b, v90
	v_exp_f32_e32 v87, v87
	v_mov_b32_dpp v92, v84 row_shr:2 row_mask:0xf bank_mask:0xf
	v_mov_b32_dpp v93, v85 row_shr:2 row_mask:0xf bank_mask:0xf
	v_mov_b32_dpp v72, v84 row_shr:1 row_mask:0xf bank_mask:0xf
	v_add_f32_e32 v87, 1.0, v87
	v_rcp_f32_e32 v87, v87
	v_mov_b32_dpp v73, v85 row_shr:1 row_mask:0xf bank_mask:0xf
	v_pk_fma_f32 v[92:93], v[126:127], v[92:93], v[142:143]
	v_mul_f32_e32 v87, v90, v87
	v_pk_fma_f32 v[72:73], v[134:135], v[72:73], v[92:93]
	v_mul_f32_e32 v86, v87, v86
	v_pk_fma_f32 v[72:73], v[84:85], v[130:131], v[72:73]
	v_mov_b32_dpp v92, v88 row_ror:1 row_mask:0xf bank_mask:0xf bound_ctrl:1
	v_mul_f32_e32 v87, 0xbfb8aa3b, v73
	v_exp_f32_e32 v87, v87
	v_mov_b32_dpp v88, v88 row_ror:2 row_mask:0xf bank_mask:0xf bound_ctrl:1
	v_mov_b32_dpp v93, v89 row_ror:1 row_mask:0xf bank_mask:0xf bound_ctrl:1
	v_mov_b32_dpp v89, v89 row_ror:2 row_mask:0xf bank_mask:0xf bound_ctrl:1
	v_add_f32_e32 v87, 1.0, v87
	v_rcp_f32_e32 v87, v87
	v_mov_b32_dpp v88, v76 row_shr:2 row_mask:0xf bank_mask:0xf
	v_mov_b32_dpp v89, v77 row_shr:2 row_mask:0xf bank_mask:0xf
	v_mov_b32_dpp v92, v76 row_shr:1 row_mask:0xf bank_mask:0xf
	v_mul_f32_e32 v73, v73, v87
	v_mul_f32_e32 v87, 0xbfb8aa3b, v72
	v_exp_f32_e32 v87, v87
; #define PG8_LAS __attribute__((address_space(3)))
; __device__ __forceinline__ unsigned cvt_pk_bf16(float lo, float hi) { unsigned r; asm volatile("v_cvt_pk_bf16_f32 %0, %1, %2" : "=v"(r) : "v"(lo), "v"(hi)); return r; }
; #define PG8_ROR(src, ctrl) __builtin_bit_cast(float, __builtin_amdgcn_mov_dpp(__builtin_bit_cast(int, (float)(src)), (ctrl), 0xf, 0xf, true))
; #define PG8_DPP(old, src, ctrl) __builtin_bit_cast(float, __builtin_amdgcn_update_dpp(__builtin_bit_cast(int, (float)(old)), __builtin_bit_cast(int, (float)(src)), (ctrl), 0xf, 0xf, false))
;     __device__ __forceinline__ void operator()(f32x4 (&acc)[2][2][4][2], const Unit& u, int wr, int wc, int fr, int fq, PG8_LAS unsigned char* lds, int wid, int lane) const {
;     ...
;         for (int n = 0; n < 2; ++n) {
;             f32x4 w[2][3], bs[2];
; #pragma unroll
;             for (int bj = 0; bj < 2; ++bj) {
; #pragma unroll
;                 for (int k = 0; k < 3; ++k) w[bj][k] = *(const f32x4*)(cw + k * 11008 + bj * 5504 + j0 + 4 * n);
;                 bs[bj] = *(const f32x4*)(cb + bj * 5504 + j0 + 4 * n); }
; #pragma unroll
;             for (int ai = 0; ai < 2; ++ai) { const int b = 2 * ai + wr;
; #pragma unroll
;                 for (int m = 0; m < 4; ++m) { f32x4 c[2];
; #pragma unroll
;                     for (int bj = 0; bj < 2; ++bj) { const f32x4 cur = acc[ai][bj][m][n]; f32x4 prev;
;                         if (m > 0) prev = acc[ai][bj][m > 0 ? m - 1 : 0][n];
;                         else { prev = (f32x4){0.f, 0.f, 0.f, 0.f}; if (b > 0 && fr >= 14) prev = *(const PG8_LAS f32x4*)(X + ((b - 1) * 2 + fr - 14) * 256 + bj * HALF + wc * 32 + 8 * fq + 4 * n); }
;                         f32x4 p1, p2;
; #pragma unroll
;                         for (int j = 0; j < 4; ++j) { const float r1 = PG8_ROR(prev[j], 0x121), r2 = PG8_ROR(prev[j], 0x122);
;                             p1[j] = PG8_DPP(r1, cur[j], 0x111); p2[j] = PG8_DPP(r2, cur[j], 0x112); }
;                         c[bj] = bs[bj] + w[bj][0] * p2 + w[bj][1] * p1 + w[bj][2] * cur; }
;                     float h4[4];
; #pragma unroll
;                     for (int j = 0; j < 4; ++j) h4[j] = c[0][j] * __builtin_amdgcn_rcpf(1.0f + __expf(-c[0][j])) * c[1][j];
;                     if (n == 0) { pk0[ai][m][0] = cvt_pk_bf16(h4[0], h4[1]); pk0[ai][m][1] = cvt_pk_bf16(h4[2], h4[3]); }
	v_mov_b32_dpp v93, v77 row_shr:1 row_mask:0xf bank_mask:0xf
	v_pk_fma_f32 v[88:89], v[114:115], v[88:89], v[138:139]
	v_add_f32_e32 v87, 1.0, v87
	v_rcp_f32_e32 v87, v87
	v_pk_fma_f32 v[88:89], v[118:119], v[92:93], v[88:89]
	v_mul_f32_e32 v72, v72, v87
	v_pk_fma_f32 v[88:89], v[76:77], v[122:123], v[88:89]
	v_mov_b32_dpp v87, v85 row_ror:1 row_mask:0xf bank_mask:0xf bound_ctrl:1
	v_mul_f32_e32 v73, v73, v89
	v_mul_f32_e32 v72, v72, v88
	v_mov_b32_dpp v88, v82 row_ror:1 row_mask:0xf bank_mask:0xf bound_ctrl:1
	v_mov_b32_dpp v82, v82 row_ror:2 row_mask:0xf bank_mask:0xf bound_ctrl:1
	v_mov_b32_dpp v89, v83 row_ror:1 row_mask:0xf bank_mask:0xf bound_ctrl:1
	v_mov_b32_dpp v83, v83 row_ror:2 row_mask:0xf bank_mask:0xf bound_ctrl:1
	v_mov_b32_dpp v82, v110 row_shr:2 row_mask:0xf bank_mask:0xf
	v_mov_b32_dpp v88, v110 row_shr:1 row_mask:0xf bank_mask:0xf
	v_mov_b32_dpp v83, v111 row_shr:2 row_mask:0xf bank_mask:0xf
	v_mov_b32_dpp v89, v111 row_shr:1 row_mask:0xf bank_mask:0xf
	v_pk_fma_f32 v[82:83], v[128:129], v[82:83], v[144:145]
	v_cvt_pk_bf16_f32 v72, v72, v73
	v_cvt_pk_bf16_f32 v73, v86, v0
	v_mov_b32_dpp v86, v84 row_ror:1 row_mask:0xf bank_mask:0xf bound_ctrl:1
	v_pk_fma_f32 v[82:83], v[136:137], v[88:89], v[82:83]
	v_mov_b32_dpp v88, v74 row_ror:1 row_mask:0xf bank_mask:0xf bound_ctrl:1
	v_pk_fma_f32 v[82:83], v[110:111], v[132:133], v[82:83]
	v_mov_b32_dpp v74, v74 row_ror:2 row_mask:0xf bank_mask:0xf bound_ctrl:1
	v_mul_f32_e32 v0, 0xbfb8aa3b, v83
	v_exp_f32_e32 v0, v0
	v_mov_b32_dpp v89, v75 row_ror:1 row_mask:0xf bank_mask:0xf bound_ctrl:1
	v_mov_b32_dpp v75, v75 row_ror:2 row_mask:0xf bank_mask:0xf bound_ctrl:1
	v_mov_b32_dpp v74, v106 row_shr:2 row_mask:0xf bank_mask:0xf
	v_add_f32_e32 v0, 1.0, v0
	v_rcp_f32_e32 v0, v0
	v_mov_b32_dpp v75, v107 row_shr:2 row_mask:0xf bank_mask:0xf
	v_mov_b32_dpp v88, v106 row_shr:1 row_mask:0xf bank_mask:0xf
	v_mov_b32_dpp v89, v107 row_shr:1 row_mask:0xf bank_mask:0xf
	v_pk_fma_f32 v[74:75], v[116:117], v[74:75], v[140:141]
	v_mul_f32_e32 v0, v83, v0
	v_pk_fma_f32 v[74:75], v[120:121], v[88:89], v[74:75]
	v_mov_b32_dpp v84, v84 row_ror:2 row_mask:0xf bank_mask:0xf bound_ctrl:1
	v_pk_fma_f32 v[74:75], v[106:107], v[124:125], v[74:75]
	v_mov_b32_dpp v85, v85 row_ror:2 row_mask:0xf bank_mask:0xf bound_ctrl:1
	v_mul_f32_e32 v0, v0, v75
	v_mul_f32_e32 v75, 0xbfb8aa3b, v82
	v_exp_f32_e32 v75, v75
	v_mov_b32_dpp v84, v108 row_shr:2 row_mask:0xf bank_mask:0xf
	v_mov_b32_dpp v85, v109 row_shr:2 row_mask:0xf bank_mask:0xf
	v_mov_b32_dpp v86, v108 row_shr:1 row_mask:0xf bank_mask:0xf
	v_add_f32_e32 v75, 1.0, v75
	v_rcp_f32_e32 v75, v75
	v_mov_b32_dpp v87, v109 row_shr:1 row_mask:0xf bank_mask:0xf
	v_pk_fma_f32 v[84:85], v[126:127], v[84:85], v[142:143]
	v_mov_b32_e32 v132, 0
	v_pk_fma_f32 v[84:85], v[134:135], v[86:87], v[84:85]
	v_mul_f32_e32 v75, v82, v75
	v_pk_fma_f32 v[84:85], v[108:109], v[130:131], v[84:85]
	v_mul_f32_e32 v74, v75, v74
	v_mul_f32_e32 v75, 0xbfb8aa3b, v85
	v_exp_f32_e32 v75, v75
	v_mov_b32_dpp v86, v76 row_ror:1 row_mask:0xf bank_mask:0xf bound_ctrl:1
	v_mov_b32_dpp v76, v76 row_ror:2 row_mask:0xf bank_mask:0xf bound_ctrl:1
	v_mov_b32_dpp v87, v77 row_ror:1 row_mask:0xf bank_mask:0xf bound_ctrl:1
	v_add_f32_e32 v75, 1.0, v75
	v_mov_b32_dpp v77, v77 row_ror:2 row_mask:0xf bank_mask:0xf bound_ctrl:1
	v_rcp_f32_e32 v75, v75
	v_mov_b32_dpp v76, v104 row_shr:2 row_mask:0xf bank_mask:0xf
	v_mov_b32_dpp v77, v105 row_shr:2 row_mask:0xf bank_mask:0xf
	v_mov_b32_dpp v86, v104 row_shr:1 row_mask:0xf bank_mask:0xf
	v_mov_b32_dpp v87, v105 row_shr:1 row_mask:0xf bank_mask:0xf
	v_pk_fma_f32 v[76:77], v[114:115], v[76:77], v[138:139]
	v_mul_f32_e32 v75, v85, v75
	v_pk_fma_f32 v[76:77], v[118:119], v[86:87], v[76:77]
	v_mov_b32_e32 v134, 0
	v_pk_fma_f32 v[76:77], v[104:105], v[122:123], v[76:77]
	v_mov_b32_e32 v135, 0
	v_mul_f32_e32 v75, v75, v77
	v_mul_f32_e32 v77, 0xbfb8aa3b, v84
	v_exp_f32_e32 v77, v77
	v_mov_b32_e32 v136, 0
	v_mov_b32_e32 v137, 0
	v_add_f32_e32 v77, 1.0, v77
	v_rcp_f32_e32 v77, v77
	s_nop 0
	v_mul_f32_e32 v77, v84, v77
	v_mul_f32_e32 v76, v77, v76
	v_cvt_pk_bf16_f32 v76, v76, v75
	v_cvt_pk_bf16_f32 v77, v74, v0
	v_add_co_u32_e32 v74, vcc, s1, v202
	global_load_dwordx4 v[92:95], v[202:203], off offset:16
	s_nop 0
	v_addc_co_u32_e32 v75, vcc, 0, v203, vcc
	global_load_dwordx4 v[116:119], v[74:75], off offset:3088
	v_add_co_u32_e32 v74, vcc, 0x15000, v202
	s_nop 1
	v_addc_co_u32_e32 v75, vcc, 0, v203, vcc
	global_load_dwordx4 v[120:123], v[74:75], off offset:2064
	global_load_dwordx4 v[128:131], v[200:201], off offset:16
	v_add_co_u32_e32 v74, vcc, 0x5000, v202
	s_nop 1
	v_addc_co_u32_e32 v75, vcc, 0, v203, vcc
	global_load_dwordx4 v[106:109], v[74:75], off offset:1552
	global_load_dwordx4 v[84:87], v[204:205], off offset:528
	v_add_co_u32_e32 v74, vcc, 0x1a000, v202
	s_nop 1
	v_addc_co_u32_e32 v75, vcc, 0, v203, vcc
	global_load_dwordx4 v[88:91], v[74:75], off offset:3600
	v_add_co_u32_e32 v74, vcc, 0x5000, v200
	s_nop 1
	v_addc_co_u32_e32 v75, vcc, 0, v201, vcc
	global_load_dwordx4 v[124:127], v[74:75], off offset:1552
	s_and_saveexec_b64 s[86:87], s[78:79]
	ds_read_b128 v[134:137], v236 offset:16
	s_or_b64 exec, exec, s[86:87]
	v_mov_b32_e32 v74, v198
	v_mov_b32_e32 v75, v198
	v_pk_mul_f32 v[62:63], v[62:63], v[74:75]
	v_pk_mul_f32 v[60:61], v[60:61], v[198:199]
	s_waitcnt lgkmcnt(0)
; #define PG8_LAS __attribute__((address_space(3)))
;     __device__ __forceinline__ void operator()(f32x4 (&acc)[2][2][4][2], const Unit& u, int wr, int wc, int fr, int fq, PG8_LAS unsigned char* lds, int wid, int lane) const {
;     ...
;         for (int n = 0; n < 2; ++n) {
;             f32x4 w[2][3], bs[2];
; #pragma unroll
;             for (int bj = 0; bj < 2; ++bj) {
; #pragma unroll
;                 for (int k = 0; k < 3; ++k) w[bj][k] = *(const f32x4*)(cw + k * 11008 + bj * 5504 + j0 + 4 * n);
;                 bs[bj] = *(const f32x4*)(cb + bj * 5504 + j0 + 4 * n); }
; #pragma unroll
;             for (int ai = 0; ai < 2; ++ai) { const int b = 2 * ai + wr;
; #pragma unroll
;                 for (int m = 0; m < 4; ++m) { f32x4 c[2];
; #pragma unroll
;                     for (int bj = 0; bj < 2; ++bj) { const f32x4 cur = acc[ai][bj][m][n]; f32x4 prev;
;                         if (m > 0) prev = acc[ai][bj][m > 0 ? m - 1 : 0][n];
;                         else { prev = (f32x4){0.f, 0.f, 0.f, 0.f}; if (b > 0 && fr >= 14) prev = *(const PG8_LAS f32x4*)(X + ((b - 1) * 2 + fr - 14) * 256 + bj * HALF + wc * 32 + 8 * fq + 4 * n); }
;                         f32x4 p1, p2;
; #pragma unroll
;                         for (int j = 0; j < 4; ++j) { const float r1 = PG8_ROR(prev[j], 0x121), r2 = PG8_ROR(prev[j], 0x122);
;                             p1[j] = PG8_DPP(r1, cur[j], 0x111); p2[j] = PG8_DPP(r2, cur[j], 0x112); }
;                         c[bj] = bs[bj] + w[bj][0] * p2 + w[bj][1] * p1 + w[bj][2] * cur; }
;                     float h4[4];
; #pragma unroll
;                     for (int j = 0; j < 4; ++j) h4[j] = c[0][j] * __builtin_amdgcn_rcpf(1.0f + __expf(-c[0][j])) * c[1][j];
;                     if (n == 0) { pk0[ai][m][0] = cvt_pk_bf16(h4[0], h4[1]); pk0[ai][m][1] = cvt_pk_bf16(h4[2], h4[3]); }
;                     else { u32x4 pk; pk.x = pk0[ai][m][0]; pk.y = pk0[ai][m][1]; pk.z = cvt_pk_bf16(h4[0], h4[1]); pk.w = cvt_pk_bf16(h4[2], h4[3]);
;                         *(PG8_LAS u32x4*)(st + fr * 80 + fq * 16) = pk;
;                         const u32x4 x = *(const PG8_LAS u32x4*)(st + (lane >> 2) * 80 + (lane & 3) * 16);
;                         const int t2 = ai * HALF + wr * 64 + m * 16 + (lane >> 2), gr = grow0 + t2;
;                         if (t2 >= 2 && gr < 8192) *(u32x4*)(HM + (size_t)gr * 5504 + u.pn * 128 + wc * 32 + 8 * (lane & 3)) = x; } } }
	v_mov_b32_dpp v82, v134 row_ror:1 row_mask:0xf bank_mask:0xf bound_ctrl:1
	v_mov_b32_dpp v98, v134 row_ror:2 row_mask:0xf bank_mask:0xf bound_ctrl:1
	v_mov_b32_dpp v83, v135 row_ror:1 row_mask:0xf bank_mask:0xf bound_ctrl:1
	v_mov_b32_dpp v99, v135 row_ror:2 row_mask:0xf bank_mask:0xf bound_ctrl:1
	v_mov_b32_dpp v104, v136 row_ror:1 row_mask:0xf bank_mask:0xf bound_ctrl:1
	v_mov_b32_dpp v110, v136 row_ror:2 row_mask:0xf bank_mask:0xf bound_ctrl:1
	v_mov_b32_dpp v105, v137 row_ror:1 row_mask:0xf bank_mask:0xf bound_ctrl:1
	v_mov_b32_dpp v111, v137 row_ror:2 row_mask:0xf bank_mask:0xf bound_ctrl:1
	v_mov_b32_dpp v82, v60 row_shr:1 row_mask:0xf bank_mask:0xf
	v_mov_b32_dpp v98, v60 row_shr:2 row_mask:0xf bank_mask:0xf
	v_mov_b32_dpp v83, v61 row_shr:1 row_mask:0xf bank_mask:0xf
	v_mov_b32_dpp v99, v61 row_shr:2 row_mask:0xf bank_mask:0xf
	v_mov_b32_dpp v104, v62 row_shr:1 row_mask:0xf bank_mask:0xf
	v_mov_b32_dpp v110, v62 row_shr:2 row_mask:0xf bank_mask:0xf
	v_mov_b32_dpp v105, v63 row_shr:1 row_mask:0xf bank_mask:0xf
	v_mov_b32_dpp v111, v63 row_shr:2 row_mask:0xf bank_mask:0xf
	v_mov_b32_e32 v133, 0
	v_mov_b32_e32 v134, 0
	v_mov_b32_e32 v135, 0
	s_and_saveexec_b64 s[86:87], s[78:79]
	ds_read_b128 v[132:135], v236 offset:528
	s_or_b64 exec, exec, s[86:87]
	s_waitcnt vmcnt(4)
	v_pk_fma_f32 v[110:111], v[94:95], v[110:111], v[130:131]
	v_pk_fma_f32 v[98:99], v[92:93], v[98:99], v[128:129]
	v_pk_fma_f32 v[104:105], v[118:119], v[104:105], v[110:111]
	v_pk_fma_f32 v[82:83], v[116:117], v[82:83], v[98:99]
	v_pk_fma_f32 v[98:99], v[62:63], v[122:123], v[104:105]
	v_pk_mul_f32 v[56:57], v[56:57], v[198:199]
	v_mul_f32_e32 v0, 0xbfb8aa3b, v99
	v_exp_f32_e32 v0, v0
	s_waitcnt lgkmcnt(0)
	v_mov_b32_dpp v104, v132 row_ror:2 row_mask:0xf bank_mask:0xf bound_ctrl:1
	v_mov_b32_dpp v105, v133 row_ror:2 row_mask:0xf bank_mask:0xf bound_ctrl:1
	v_pk_mul_f32 v[58:59], v[58:59], v[74:75]
	v_mov_b32_dpp v74, v132 row_ror:1 row_mask:0xf bank_mask:0xf bound_ctrl:1
	v_mov_b32_dpp v104, v56 row_shr:2 row_mask:0xf bank_mask:0xf
	v_mov_b32_dpp v75, v133 row_ror:1 row_mask:0xf bank_mask:0xf bound_ctrl:1
	v_mov_b32_dpp v105, v57 row_shr:2 row_mask:0xf bank_mask:0xf
	v_mov_b32_dpp v114, v134 row_ror:2 row_mask:0xf bank_mask:0xf bound_ctrl:1
	v_mov_b32_dpp v115, v135 row_ror:2 row_mask:0xf bank_mask:0xf bound_ctrl:1
	v_mov_b32_dpp v74, v56 row_shr:1 row_mask:0xf bank_mask:0xf
	v_mov_b32_dpp v75, v57 row_shr:1 row_mask:0xf bank_mask:0xf
	v_mov_b32_dpp v110, v134 row_ror:1 row_mask:0xf bank_mask:0xf bound_ctrl:1
	v_mov_b32_dpp v114, v58 row_shr:2 row_mask:0xf bank_mask:0xf
	v_mov_b32_dpp v111, v135 row_ror:1 row_mask:0xf bank_mask:0xf bound_ctrl:1
	v_mov_b32_dpp v115, v59 row_shr:2 row_mask:0xf bank_mask:0xf
	s_waitcnt vmcnt(0)
	v_pk_fma_f32 v[104:105], v[106:107], v[104:105], v[124:125]
	v_add_f32_e32 v0, 1.0, v0
	v_mov_b32_dpp v110, v58 row_shr:1 row_mask:0xf bank_mask:0xf
	v_mov_b32_dpp v111, v59 row_shr:1 row_mask:0xf bank_mask:0xf
	v_pk_fma_f32 v[114:115], v[108:109], v[114:115], v[126:127]
	v_pk_fma_f32 v[74:75], v[84:85], v[74:75], v[104:105]
	v_rcp_f32_e32 v0, v0
	v_mul_f32_e32 v104, 0xbfb8aa3b, v98
	v_pk_fma_f32 v[110:111], v[86:87], v[110:111], v[114:115]
	v_exp_f32_e32 v114, v104
	v_pk_fma_f32 v[82:83], v[60:61], v[120:121], v[82:83]
	v_pk_fma_f32 v[104:105], v[58:59], v[90:91], v[110:111]
	v_mul_f32_e32 v0, v99, v0
	v_mul_f32_e32 v0, v0, v105
	v_add_f32_e32 v99, 1.0, v114
	v_mul_f32_e32 v105, 0xbfb8aa3b, v83
	v_mul_f32_e32 v110, 0xbfb8aa3b, v82
	v_rcp_f32_e32 v99, v99
	v_exp_f32_e32 v105, v105
	v_exp_f32_e32 v110, v110
	v_pk_fma_f32 v[74:75], v[56:57], v[88:89], v[74:75]
	v_mul_f32_e32 v98, v98, v99
	v_add_f32_e32 v99, 1.0, v105
	v_add_f32_e32 v105, 1.0, v110
	v_rcp_f32_e32 v105, v105
	v_rcp_f32_e32 v99, v99
	s_ashr_i32 s1, s0, 31
	v_mul_f32_e32 v98, v98, v104
	v_mul_f32_e32 v82, v82, v105
	v_mul_f32_e32 v83, v83, v99
	v_mul_f32_e32 v74, v82, v74
	v_mul_f32_e32 v75, v83, v75
	v_cvt_pk_bf16_f32 v114, v74, v75
	v_add_u32_e32 v74, s72, v235
	v_cmp_gt_i32_e32 vcc, s37, v74
	v_cvt_pk_bf16_f32 v115, v98, v0
	s_and_b64 s[88:89], s[42:43], vcc
	v_lshlrev_b32_e32 v0, 1, v182
	ds_write_b128 v240, v[112:115]
	s_and_saveexec_b64 s[86:87], s[88:89]
	s_cbranch_execz .LBB0_391
	ds_read_b128 v[110:113], v241
	v_mov_b64_e32 v[82:83], s[12:13]
	s_movk_i32 s20, 0x2b00
	v_mad_i64_i32 v[74:75], s[88:89], v74, s20, v[82:83]
	v_lshl_add_u64 v[74:75], s[0:1], 1, v[74:75]
	s_lshl_b32 s20, s97, 1
	v_lshl_add_u64 v[74:75], v[74:75], 0, s[20:21]
	v_lshl_add_u64 v[74:75], v[74:75], 0, v[0:1]
	s_waitcnt lgkmcnt(0)
	global_store_dwordx4 v[74:75], v[110:113], off nt
; #define PG8_LAS __attribute__((address_space(3)))
;     __device__ __forceinline__ void operator()(f32x4 (&acc)[2][2][4][2], const Unit& u, int wr, int wc, int fr, int fq, PG8_LAS unsigned char* lds, int wid, int lane) const {
;     ...
;         for (int n = 0; n < 2; ++n) {
;             f32x4 w[2][3], bs[2];
; #pragma unroll
;             for (int bj = 0; bj < 2; ++bj) {
; #pragma unroll
;                 for (int k = 0; k < 3; ++k) w[bj][k] = *(const f32x4*)(cw + k * 11008 + bj * 5504 + j0 + 4 * n);
;                 bs[bj] = *(const f32x4*)(cb + bj * 5504 + j0 + 4 * n); }
; #pragma unroll
;             for (int ai = 0; ai < 2; ++ai) { const int b = 2 * ai + wr;
; #pragma unroll
;                 for (int m = 0; m < 4; ++m) { f32x4 c[2];
; #pragma unroll
;                     for (int bj = 0; bj < 2; ++bj) { const f32x4 cur = acc[ai][bj][m][n]; f32x4 prev;
;                         if (m > 0) prev = acc[ai][bj][m > 0 ? m - 1 : 0][n];
;                         else { prev = (f32x4){0.f, 0.f, 0.f, 0.f}; if (b > 0 && fr >= 14) prev = *(const PG8_LAS f32x4*)(X + ((b - 1) * 2 + fr - 14) * 256 + bj * HALF + wc * 32 + 8 * fq + 4 * n); }
;                         f32x4 p1, p2;
; #pragma unroll
;                         for (int j = 0; j < 4; ++j) { const float r1 = PG8_ROR(prev[j], 0x121), r2 = PG8_ROR(prev[j], 0x122);
;                             p1[j] = PG8_DPP(r1, cur[j], 0x111); p2[j] = PG8_DPP(r2, cur[j], 0x112); }
;                         c[bj] = bs[bj] + w[bj][0] * p2 + w[bj][1] * p1 + w[bj][2] * cur; }
;                     float h4[4];
; #pragma unroll
;                     for (int j = 0; j < 4; ++j) h4[j] = c[0][j] * __builtin_amdgcn_rcpf(1.0f + __expf(-c[0][j])) * c[1][j];
;                     if (n == 0) { pk0[ai][m][0] = cvt_pk_bf16(h4[0], h4[1]); pk0[ai][m][1] = cvt_pk_bf16(h4[2], h4[3]); }
;                     else { u32x4 pk; pk.x = pk0[ai][m][0]; pk.y = pk0[ai][m][1]; pk.z = cvt_pk_bf16(h4[0], h4[1]); pk.w = cvt_pk_bf16(h4[2], h4[3]);
;                         *(PG8_LAS u32x4*)(st + fr * 80 + fq * 16) = pk;
;                         const u32x4 x = *(const PG8_LAS u32x4*)(st + (lane >> 2) * 80 + (lane & 3) * 16);
;                         const int t2 = ai * HALF + wr * 64 + m * 16 + (lane >> 2), gr = grow0 + t2;
;                         if (t2 >= 2 && gr < 8192) *(u32x4*)(HM + (size_t)gr * 5504 + u.pn * 128 + wc * 32 + 8 * (lane & 3)) = x; } } }
.LBB0_391:
	s_or_b64 exec, exec, s[86:87]
	v_mov_b32_e32 v197, v196
	v_mov_b32_e32 v74, v196
	v_mov_b32_e32 v75, v196
	v_pk_mul_f32 v[54:55], v[54:55], v[74:75]
	v_pk_mul_f32 v[52:53], v[52:53], v[196:197]
	v_pk_mul_f32 v[50:51], v[50:51], v[74:75]
	v_mov_b32_dpp v74, v60 row_ror:1 row_mask:0xf bank_mask:0xf bound_ctrl:1
	v_mov_b32_dpp v60, v60 row_ror:2 row_mask:0xf bank_mask:0xf bound_ctrl:1
	v_mov_b32_dpp v75, v61 row_ror:1 row_mask:0xf bank_mask:0xf bound_ctrl:1
	v_mov_b32_dpp v61, v61 row_ror:2 row_mask:0xf bank_mask:0xf bound_ctrl:1
	v_mov_b32_dpp v60, v52 row_shr:2 row_mask:0xf bank_mask:0xf
	v_mov_b32_dpp v82, v62 row_ror:1 row_mask:0xf bank_mask:0xf bound_ctrl:1
	v_mov_b32_dpp v61, v53 row_shr:2 row_mask:0xf bank_mask:0xf
	v_mov_b32_dpp v62, v62 row_ror:2 row_mask:0xf bank_mask:0xf bound_ctrl:1
	v_mov_b32_dpp v83, v63 row_ror:1 row_mask:0xf bank_mask:0xf bound_ctrl:1
	v_mov_b32_dpp v63, v63 row_ror:2 row_mask:0xf bank_mask:0xf bound_ctrl:1
	v_mov_b32_dpp v74, v52 row_shr:1 row_mask:0xf bank_mask:0xf
	v_mov_b32_dpp v75, v53 row_shr:1 row_mask:0xf bank_mask:0xf
	v_mov_b32_dpp v62, v54 row_shr:2 row_mask:0xf bank_mask:0xf
	v_mov_b32_dpp v63, v55 row_shr:2 row_mask:0xf bank_mask:0xf
	v_pk_fma_f32 v[60:61], v[92:93], v[60:61], v[128:129]
	v_pk_mul_f32 v[48:49], v[48:49], v[196:197]
	v_mov_b32_dpp v82, v54 row_shr:1 row_mask:0xf bank_mask:0xf
	v_mov_b32_dpp v83, v55 row_shr:1 row_mask:0xf bank_mask:0xf
	v_pk_fma_f32 v[62:63], v[94:95], v[62:63], v[130:131]
	v_pk_fma_f32 v[60:61], v[116:117], v[74:75], v[60:61]
	v_mov_b32_dpp v74, v56 row_ror:1 row_mask:0xf bank_mask:0xf bound_ctrl:1
	v_mov_b32_dpp v56, v56 row_ror:2 row_mask:0xf bank_mask:0xf bound_ctrl:1
	v_mov_b32_dpp v75, v57 row_ror:1 row_mask:0xf bank_mask:0xf bound_ctrl:1
	v_mov_b32_dpp v57, v57 row_ror:2 row_mask:0xf bank_mask:0xf bound_ctrl:1
	v_pk_fma_f32 v[62:63], v[118:119], v[82:83], v[62:63]
	v_mov_b32_dpp v56, v48 row_shr:2 row_mask:0xf bank_mask:0xf
	v_mov_b32_dpp v57, v49 row_shr:2 row_mask:0xf bank_mask:0xf
	v_pk_fma_f32 v[62:63], v[54:55], v[122:123], v[62:63]
	v_mov_b32_dpp v74, v48 row_shr:1 row_mask:0xf bank_mask:0xf
	v_mov_b32_dpp v75, v49 row_shr:1 row_mask:0xf bank_mask:0xf
	v_pk_fma_f32 v[56:57], v[106:107], v[56:57], v[124:125]
	v_mov_b32_dpp v82, v58 row_ror:1 row_mask:0xf bank_mask:0xf bound_ctrl:1
	v_pk_fma_f32 v[56:57], v[84:85], v[74:75], v[56:57]
	v_mul_f32_e32 v74, 0xbfb8aa3b, v63
	v_exp_f32_e32 v74, v74
	v_mov_b32_dpp v58, v58 row_ror:2 row_mask:0xf bank_mask:0xf bound_ctrl:1
	v_mov_b32_dpp v83, v59 row_ror:1 row_mask:0xf bank_mask:0xf bound_ctrl:1
	v_mov_b32_dpp v59, v59 row_ror:2 row_mask:0xf bank_mask:0xf bound_ctrl:1
	v_add_f32_e32 v74, 1.0, v74
	v_rcp_f32_e32 v74, v74
	v_mov_b32_dpp v58, v50 row_shr:2 row_mask:0xf bank_mask:0xf
	v_mov_b32_dpp v59, v51 row_shr:2 row_mask:0xf bank_mask:0xf
	v_mov_b32_dpp v82, v50 row_shr:1 row_mask:0xf bank_mask:0xf
	v_mov_b32_dpp v83, v51 row_shr:1 row_mask:0xf bank_mask:0xf
	v_pk_fma_f32 v[58:59], v[108:109], v[58:59], v[126:127]
	v_mul_f32_e32 v63, v63, v74
	v_pk_fma_f32 v[58:59], v[86:87], v[82:83], v[58:59]
	v_pk_fma_f32 v[60:61], v[52:53], v[120:121], v[60:61]
	v_pk_fma_f32 v[58:59], v[50:51], v[90:91], v[58:59]
	v_pk_fma_f32 v[56:57], v[48:49], v[88:89], v[56:57]
	v_mul_f32_e32 v59, v63, v59
	v_mul_f32_e32 v63, 0xbfb8aa3b, v62
	v_exp_f32_e32 v63, v63
	s_nop 0
	v_add_f32_e32 v63, 1.0, v63
	v_rcp_f32_e32 v63, v63
	s_nop 0
	v_mul_f32_e32 v62, v62, v63
	v_mul_f32_e32 v58, v62, v58
	v_mul_f32_e32 v62, 0xbfb8aa3b, v61
	v_exp_f32_e32 v62, v62
	s_nop 0
	v_add_f32_e32 v62, 1.0, v62
	v_rcp_f32_e32 v62, v62
	s_nop 0
	v_mul_f32_e32 v61, v61, v62
	v_mul_f32_e32 v57, v61, v57
	v_mul_f32_e32 v61, 0xbfb8aa3b, v60
	v_exp_f32_e32 v61, v61
	s_nop 0
	v_add_f32_e32 v61, 1.0, v61
	v_rcp_f32_e32 v61, v61
	s_nop 0
	v_mul_f32_e32 v60, v60, v61
	v_mul_f32_e32 v56, v60, v56
	v_cvt_pk_bf16_f32 v104, v56, v57
	v_or_b32_e32 v56, 16, v235
	v_add_u32_e32 v56, s72, v56
	v_cmp_gt_i32_e32 vcc, s37, v56
	s_and_b64 s[88:89], s[82:83], vcc
	v_cvt_pk_bf16_f32 v105, v58, v59
	ds_write_b128 v240, v[102:105]
	s_and_saveexec_b64 s[86:87], s[88:89]
	s_cbranch_execz .LBB0_393
	ds_read_b128 v[58:61], v241
	v_mov_b64_e32 v[62:63], s[12:13]
	s_movk_i32 s20, 0x2b00
	v_mad_i64_i32 v[56:57], s[88:89], v56, s20, v[62:63]
	v_lshl_add_u64 v[56:57], s[0:1], 1, v[56:57]
	s_lshl_b32 s20, s97, 1
	v_lshl_add_u64 v[56:57], v[56:57], 0, s[20:21]
	v_lshl_add_u64 v[56:57], v[56:57], 0, v[0:1]
	s_waitcnt lgkmcnt(0)
	global_store_dwordx4 v[56:57], v[58:61], off nt
; #define PG8_LAS __attribute__((address_space(3)))
;     __device__ __forceinline__ void operator()(f32x4 (&acc)[2][2][4][2], const Unit& u, int wr, int wc, int fr, int fq, PG8_LAS unsigned char* lds, int wid, int lane) const {
;     ...
;         for (int n = 0; n < 2; ++n) {
;             f32x4 w[2][3], bs[2];
; #pragma unroll
;             for (int bj = 0; bj < 2; ++bj) {
; #pragma unroll
;                 for (int k = 0; k < 3; ++k) w[bj][k] = *(const f32x4*)(cw + k * 11008 + bj * 5504 + j0 + 4 * n);
;                 bs[bj] = *(const f32x4*)(cb + bj * 5504 + j0 + 4 * n); }
; #pragma unroll
;             for (int ai = 0; ai < 2; ++ai) { const int b = 2 * ai + wr;
; #pragma unroll
;                 for (int m = 0; m < 4; ++m) { f32x4 c[2];
; #pragma unroll
;                     for (int bj = 0; bj < 2; ++bj) { const f32x4 cur = acc[ai][bj][m][n]; f32x4 prev;
;                         if (m > 0) prev = acc[ai][bj][m > 0 ? m - 1 : 0][n];
;                         else { prev = (f32x4){0.f, 0.f, 0.f, 0.f}; if (b > 0 && fr >= 14) prev = *(const PG8_LAS f32x4*)(X + ((b - 1) * 2 + fr - 14) * 256 + bj * HALF + wc * 32 + 8 * fq + 4 * n); }
;                         f32x4 p1, p2;
; #pragma unroll
;                         for (int j = 0; j < 4; ++j) { const float r1 = PG8_ROR(prev[j], 0x121), r2 = PG8_ROR(prev[j], 0x122);
;                             p1[j] = PG8_DPP(r1, cur[j], 0x111); p2[j] = PG8_DPP(r2, cur[j], 0x112); }
;                         c[bj] = bs[bj] + w[bj][0] * p2 + w[bj][1] * p1 + w[bj][2] * cur; }
;                     float h4[4];
; #pragma unroll
;                     for (int j = 0; j < 4; ++j) h4[j] = c[0][j] * __builtin_amdgcn_rcpf(1.0f + __expf(-c[0][j])) * c[1][j];
;                     if (n == 0) { pk0[ai][m][0] = cvt_pk_bf16(h4[0], h4[1]); pk0[ai][m][1] = cvt_pk_bf16(h4[2], h4[3]); }
;                     else { u32x4 pk; pk.x = pk0[ai][m][0]; pk.y = pk0[ai][m][1]; pk.z = cvt_pk_bf16(h4[0], h4[1]); pk.w = cvt_pk_bf16(h4[2], h4[3]);
;                         *(PG8_LAS u32x4*)(st + fr * 80 + fq * 16) = pk;
;                         const u32x4 x = *(const PG8_LAS u32x4*)(st + (lane >> 2) * 80 + (lane & 3) * 16);
;                         const int t2 = ai * HALF + wr * 64 + m * 16 + (lane >> 2), gr = grow0 + t2;
;                         if (t2 >= 2 && gr < 8192) *(u32x4*)(HM + (size_t)gr * 5504 + u.pn * 128 + wc * 32 + 8 * (lane & 3)) = x; } } }
.LBB0_393:
	s_or_b64 exec, exec, s[86:87]
	v_mov_b32_e32 v195, v194
	v_mov_b32_e32 v56, v194
	v_mov_b32_e32 v57, v194
	v_pk_mul_f32 v[38:39], v[38:39], v[56:57]
	v_pk_mul_f32 v[36:37], v[36:37], v[194:195]
	v_pk_mul_f32 v[34:35], v[34:35], v[56:57]
	v_mov_b32_dpp v56, v52 row_ror:1 row_mask:0xf bank_mask:0xf bound_ctrl:1
	v_mov_b32_dpp v52, v52 row_ror:2 row_mask:0xf bank_mask:0xf bound_ctrl:1
	v_mov_b32_dpp v57, v53 row_ror:1 row_mask:0xf bank_mask:0xf bound_ctrl:1
	v_mov_b32_dpp v53, v53 row_ror:2 row_mask:0xf bank_mask:0xf bound_ctrl:1
	v_mov_b32_dpp v52, v36 row_shr:2 row_mask:0xf bank_mask:0xf
	v_mov_b32_dpp v58, v54 row_ror:1 row_mask:0xf bank_mask:0xf bound_ctrl:1
	v_mov_b32_dpp v53, v37 row_shr:2 row_mask:0xf bank_mask:0xf
	v_mov_b32_dpp v54, v54 row_ror:2 row_mask:0xf bank_mask:0xf bound_ctrl:1
	v_mov_b32_dpp v59, v55 row_ror:1 row_mask:0xf bank_mask:0xf bound_ctrl:1
	v_mov_b32_dpp v55, v55 row_ror:2 row_mask:0xf bank_mask:0xf bound_ctrl:1
	v_mov_b32_dpp v56, v36 row_shr:1 row_mask:0xf bank_mask:0xf
	v_mov_b32_dpp v57, v37 row_shr:1 row_mask:0xf bank_mask:0xf
	v_mov_b32_dpp v54, v38 row_shr:2 row_mask:0xf bank_mask:0xf
	v_mov_b32_dpp v55, v39 row_shr:2 row_mask:0xf bank_mask:0xf
	v_pk_fma_f32 v[52:53], v[92:93], v[52:53], v[128:129]
	v_pk_mul_f32 v[32:33], v[32:33], v[194:195]
	v_mov_b32_dpp v58, v38 row_shr:1 row_mask:0xf bank_mask:0xf
	v_mov_b32_dpp v59, v39 row_shr:1 row_mask:0xf bank_mask:0xf
	v_pk_fma_f32 v[54:55], v[94:95], v[54:55], v[130:131]
	v_pk_fma_f32 v[52:53], v[116:117], v[56:57], v[52:53]
	v_mov_b32_dpp v56, v48 row_ror:1 row_mask:0xf bank_mask:0xf bound_ctrl:1
	v_mov_b32_dpp v48, v48 row_ror:2 row_mask:0xf bank_mask:0xf bound_ctrl:1
	v_mov_b32_dpp v57, v49 row_ror:1 row_mask:0xf bank_mask:0xf bound_ctrl:1
	v_mov_b32_dpp v49, v49 row_ror:2 row_mask:0xf bank_mask:0xf bound_ctrl:1
	v_pk_fma_f32 v[54:55], v[118:119], v[58:59], v[54:55]
	v_mov_b32_dpp v48, v32 row_shr:2 row_mask:0xf bank_mask:0xf
	v_mov_b32_dpp v49, v33 row_shr:2 row_mask:0xf bank_mask:0xf
	v_pk_fma_f32 v[54:55], v[38:39], v[122:123], v[54:55]
	v_mov_b32_dpp v56, v32 row_shr:1 row_mask:0xf bank_mask:0xf
	v_mov_b32_dpp v57, v33 row_shr:1 row_mask:0xf bank_mask:0xf
	v_pk_fma_f32 v[48:49], v[106:107], v[48:49], v[124:125]
	v_mov_b32_dpp v58, v50 row_ror:1 row_mask:0xf bank_mask:0xf bound_ctrl:1
	v_pk_fma_f32 v[48:49], v[84:85], v[56:57], v[48:49]
	v_mul_f32_e32 v56, 0xbfb8aa3b, v55
	v_exp_f32_e32 v56, v56
	v_mov_b32_dpp v50, v50 row_ror:2 row_mask:0xf bank_mask:0xf bound_ctrl:1
	v_mov_b32_dpp v59, v51 row_ror:1 row_mask:0xf bank_mask:0xf bound_ctrl:1
	v_mov_b32_dpp v51, v51 row_ror:2 row_mask:0xf bank_mask:0xf bound_ctrl:1
	v_add_f32_e32 v56, 1.0, v56
	v_rcp_f32_e32 v56, v56
	v_mov_b32_dpp v50, v34 row_shr:2 row_mask:0xf bank_mask:0xf
	v_mov_b32_dpp v51, v35 row_shr:2 row_mask:0xf bank_mask:0xf
	v_mov_b32_dpp v58, v34 row_shr:1 row_mask:0xf bank_mask:0xf
	v_mov_b32_dpp v59, v35 row_shr:1 row_mask:0xf bank_mask:0xf
	v_pk_fma_f32 v[50:51], v[108:109], v[50:51], v[126:127]
	v_mul_f32_e32 v55, v55, v56
	v_pk_fma_f32 v[50:51], v[86:87], v[58:59], v[50:51]
	v_pk_fma_f32 v[52:53], v[36:37], v[120:121], v[52:53]
	v_pk_fma_f32 v[50:51], v[34:35], v[90:91], v[50:51]
	v_pk_fma_f32 v[48:49], v[32:33], v[88:89], v[48:49]
	v_mul_f32_e32 v51, v55, v51
	v_mul_f32_e32 v55, 0xbfb8aa3b, v54
	v_exp_f32_e32 v55, v55
	s_nop 0
	v_add_f32_e32 v55, 1.0, v55
	v_rcp_f32_e32 v55, v55
	s_nop 0
	v_mul_f32_e32 v54, v54, v55
	v_mul_f32_e32 v50, v54, v50
	v_mul_f32_e32 v54, 0xbfb8aa3b, v53
	v_exp_f32_e32 v54, v54
	s_nop 0
	v_add_f32_e32 v54, 1.0, v54
	v_rcp_f32_e32 v54, v54
	s_nop 0
	v_mul_f32_e32 v53, v53, v54
	v_mul_f32_e32 v49, v53, v49
	v_mul_f32_e32 v53, 0xbfb8aa3b, v52
	v_exp_f32_e32 v53, v53
	s_nop 0
	v_add_f32_e32 v53, 1.0, v53
	v_rcp_f32_e32 v53, v53
	s_nop 0
	v_mul_f32_e32 v52, v52, v53
	v_mul_f32_e32 v48, v52, v48
	v_cvt_pk_bf16_f32 v98, v48, v49
	v_or_b32_e32 v48, 32, v235
	v_add_u32_e32 v48, s72, v48
	v_cmp_gt_i32_e32 vcc, s37, v48
	s_and_b64 s[88:89], s[82:83], vcc
	v_cvt_pk_bf16_f32 v99, v50, v51
	ds_write_b128 v240, v[96:99]
	s_and_saveexec_b64 s[86:87], s[88:89]
	s_cbranch_execz .LBB0_395
	ds_read_b128 v[50:53], v241
	v_mov_b64_e32 v[54:55], s[12:13]
	s_movk_i32 s20, 0x2b00
	v_mad_i64_i32 v[48:49], s[88:89], v48, s20, v[54:55]
	v_lshl_add_u64 v[48:49], s[0:1], 1, v[48:49]
	s_lshl_b32 s20, s97, 1
	v_lshl_add_u64 v[48:49], v[48:49], 0, s[20:21]
	v_lshl_add_u64 v[48:49], v[48:49], 0, v[0:1]
	s_waitcnt lgkmcnt(0)
	global_store_dwordx4 v[48:49], v[50:53], off nt
; #define PG8_LAS __attribute__((address_space(3)))
;     __device__ __forceinline__ void operator()(f32x4 (&acc)[2][2][4][2], const Unit& u, int wr, int wc, int fr, int fq, PG8_LAS unsigned char* lds, int wid, int lane) const {
;     ...
;         for (int n = 0; n < 2; ++n) {
;             f32x4 w[2][3], bs[2];
; #pragma unroll
;             for (int bj = 0; bj < 2; ++bj) {
; #pragma unroll
;                 for (int k = 0; k < 3; ++k) w[bj][k] = *(const f32x4*)(cw + k * 11008 + bj * 5504 + j0 + 4 * n);
;                 bs[bj] = *(const f32x4*)(cb + bj * 5504 + j0 + 4 * n); }
; #pragma unroll
;             for (int ai = 0; ai < 2; ++ai) { const int b = 2 * ai + wr;
; #pragma unroll
;                 for (int m = 0; m < 4; ++m) { f32x4 c[2];
; #pragma unroll
;                     for (int bj = 0; bj < 2; ++bj) { const f32x4 cur = acc[ai][bj][m][n]; f32x4 prev;
;                         if (m > 0) prev = acc[ai][bj][m > 0 ? m - 1 : 0][n];
;                         else { prev = (f32x4){0.f, 0.f, 0.f, 0.f}; if (b > 0 && fr >= 14) prev = *(const PG8_LAS f32x4*)(X + ((b - 1) * 2 + fr - 14) * 256 + bj * HALF + wc * 32 + 8 * fq + 4 * n); }
;                         f32x4 p1, p2;
; #pragma unroll
;                         for (int j = 0; j < 4; ++j) { const float r1 = PG8_ROR(prev[j], 0x121), r2 = PG8_ROR(prev[j], 0x122);
;                             p1[j] = PG8_DPP(r1, cur[j], 0x111); p2[j] = PG8_DPP(r2, cur[j], 0x112); }
;                         c[bj] = bs[bj] + w[bj][0] * p2 + w[bj][1] * p1 + w[bj][2] * cur; }
;                     float h4[4];
; #pragma unroll
;                     for (int j = 0; j < 4; ++j) h4[j] = c[0][j] * __builtin_amdgcn_rcpf(1.0f + __expf(-c[0][j])) * c[1][j];
;                     if (n == 0) { pk0[ai][m][0] = cvt_pk_bf16(h4[0], h4[1]); pk0[ai][m][1] = cvt_pk_bf16(h4[2], h4[3]); }
;                     else { u32x4 pk; pk.x = pk0[ai][m][0]; pk.y = pk0[ai][m][1]; pk.z = cvt_pk_bf16(h4[0], h4[1]); pk.w = cvt_pk_bf16(h4[2], h4[3]);
;                         *(PG8_LAS u32x4*)(st + fr * 80 + fq * 16) = pk;
;                         const u32x4 x = *(const PG8_LAS u32x4*)(st + (lane >> 2) * 80 + (lane & 3) * 16);
;                         const int t2 = ai * HALF + wr * 64 + m * 16 + (lane >> 2), gr = grow0 + t2;
;                         if (t2 >= 2 && gr < 8192) *(u32x4*)(HM + (size_t)gr * 5504 + u.pn * 128 + wc * 32 + 8 * (lane & 3)) = x; } } }
.LBB0_395:
	s_or_b64 exec, exec, s[86:87]
	s_nop 0
	v_mov_b32_dpp v50, v38 row_ror:1 row_mask:0xf bank_mask:0xf bound_ctrl:1
	v_mov_b32_dpp v38, v38 row_ror:2 row_mask:0xf bank_mask:0xf bound_ctrl:1
	v_mov_b32_dpp v51, v39 row_ror:1 row_mask:0xf bank_mask:0xf bound_ctrl:1
	v_mov_b32_dpp v39, v39 row_ror:2 row_mask:0xf bank_mask:0xf bound_ctrl:1
	v_mov_b32_dpp v38, v70 row_shr:2 row_mask:0xf bank_mask:0xf
	v_mov_b32_dpp v50, v70 row_shr:1 row_mask:0xf bank_mask:0xf
	v_mov_b32_dpp v39, v71 row_shr:2 row_mask:0xf bank_mask:0xf
	v_mov_b32_dpp v51, v71 row_shr:1 row_mask:0xf bank_mask:0xf
	v_pk_fma_f32 v[38:39], v[94:95], v[38:39], v[130:131]
	v_mov_b32_dpp v48, v36 row_ror:1 row_mask:0xf bank_mask:0xf bound_ctrl:1
	v_pk_fma_f32 v[38:39], v[118:119], v[50:51], v[38:39]
	v_mov_b32_dpp v36, v36 row_ror:2 row_mask:0xf bank_mask:0xf bound_ctrl:1
	v_mov_b32_dpp v49, v37 row_ror:1 row_mask:0xf bank_mask:0xf bound_ctrl:1
	v_mov_b32_dpp v37, v37 row_ror:2 row_mask:0xf bank_mask:0xf bound_ctrl:1
	v_pk_fma_f32 v[38:39], v[70:71], v[122:123], v[38:39]
	v_mov_b32_dpp v36, v68 row_shr:2 row_mask:0xf bank_mask:0xf
	v_mov_b32_dpp v37, v69 row_shr:2 row_mask:0xf bank_mask:0xf
	v_mul_f32_e32 v52, 0xbfb8aa3b, v39
	v_mov_b32_dpp v48, v68 row_shr:1 row_mask:0xf bank_mask:0xf
	v_mov_b32_dpp v49, v69 row_shr:1 row_mask:0xf bank_mask:0xf
	v_pk_fma_f32 v[36:37], v[92:93], v[36:37], v[128:129]
	v_exp_f32_e32 v52, v52
	v_pk_fma_f32 v[36:37], v[116:117], v[48:49], v[36:37]
	v_mov_b32_dpp v48, v32 row_ror:1 row_mask:0xf bank_mask:0xf bound_ctrl:1
	v_mov_b32_dpp v32, v32 row_ror:2 row_mask:0xf bank_mask:0xf bound_ctrl:1
	v_mov_b32_dpp v49, v33 row_ror:1 row_mask:0xf bank_mask:0xf bound_ctrl:1
	v_mov_b32_dpp v33, v33 row_ror:2 row_mask:0xf bank_mask:0xf bound_ctrl:1
	v_mov_b32_dpp v32, v64 row_shr:2 row_mask:0xf bank_mask:0xf
	v_mov_b32_dpp v48, v64 row_shr:1 row_mask:0xf bank_mask:0xf
	v_mov_b32_dpp v33, v65 row_shr:2 row_mask:0xf bank_mask:0xf
	v_mov_b32_dpp v49, v65 row_shr:1 row_mask:0xf bank_mask:0xf
	v_pk_fma_f32 v[32:33], v[106:107], v[32:33], v[124:125]
	v_mov_b32_dpp v50, v34 row_ror:1 row_mask:0xf bank_mask:0xf bound_ctrl:1
	v_pk_fma_f32 v[32:33], v[84:85], v[48:49], v[32:33]
	v_add_f32_e32 v48, 1.0, v52
	v_mov_b32_dpp v34, v34 row_ror:2 row_mask:0xf bank_mask:0xf bound_ctrl:1
	v_mov_b32_dpp v51, v35 row_ror:1 row_mask:0xf bank_mask:0xf bound_ctrl:1
	v_mov_b32_dpp v35, v35 row_ror:2 row_mask:0xf bank_mask:0xf bound_ctrl:1
	v_rcp_f32_e32 v48, v48
	v_mul_f32_e32 v49, 0xbfb8aa3b, v38
	v_mov_b32_dpp v34, v66 row_shr:2 row_mask:0xf bank_mask:0xf
	v_mov_b32_dpp v35, v67 row_shr:2 row_mask:0xf bank_mask:0xf
	v_exp_f32_e32 v49, v49
	v_mov_b32_dpp v50, v66 row_shr:1 row_mask:0xf bank_mask:0xf
	v_mov_b32_dpp v51, v67 row_shr:1 row_mask:0xf bank_mask:0xf
	v_pk_fma_f32 v[34:35], v[108:109], v[34:35], v[126:127]
	v_pk_fma_f32 v[36:37], v[68:69], v[120:121], v[36:37]
	v_pk_fma_f32 v[34:35], v[86:87], v[50:51], v[34:35]
	v_mul_f32_e32 v39, v39, v48
	v_pk_fma_f32 v[34:35], v[66:67], v[90:91], v[34:35]
	v_mul_f32_e32 v48, 0xbfb8aa3b, v37
	v_mul_f32_e32 v35, v39, v35
	v_add_f32_e32 v39, 1.0, v49
	v_mul_f32_e32 v49, 0xbfb8aa3b, v36
	v_rcp_f32_e32 v39, v39
	v_exp_f32_e32 v48, v48
	v_exp_f32_e32 v49, v49
	v_pk_fma_f32 v[32:33], v[64:65], v[88:89], v[32:33]
	v_mul_f32_e32 v38, v38, v39
	v_add_f32_e32 v39, 1.0, v48
	v_add_f32_e32 v48, 1.0, v49
	v_rcp_f32_e32 v48, v48
	v_rcp_f32_e32 v39, v39
	v_mul_f32_e32 v34, v38, v34
	v_mul_f32_e32 v36, v36, v48
	v_mul_f32_e32 v37, v37, v39
	v_mul_f32_e32 v32, v36, v32
	v_mul_f32_e32 v33, v37, v33
	v_cvt_pk_bf16_f32 v102, v32, v33
	v_or_b32_e32 v32, 48, v235
	v_add_u32_e32 v32, s72, v32
	v_cmp_gt_i32_e32 vcc, s37, v32
	s_and_b64 s[88:89], s[82:83], vcc
	v_cvt_pk_bf16_f32 v103, v34, v35
	ds_write_b128 v240, v[100:103]
	s_and_saveexec_b64 s[86:87], s[88:89]
	s_cbranch_execz .LBB0_397
	ds_read_b128 v[34:37], v241
	v_mov_b64_e32 v[38:39], s[12:13]
	s_movk_i32 s20, 0x2b00
	v_mad_i64_i32 v[32:33], s[88:89], v32, s20, v[38:39]
	v_lshl_add_u64 v[32:33], s[0:1], 1, v[32:33]
	s_lshl_b32 s20, s97, 1
	v_lshl_add_u64 v[32:33], v[32:33], 0, s[20:21]
	v_lshl_add_u64 v[32:33], v[32:33], 0, v[0:1]
	s_waitcnt lgkmcnt(0)
	global_store_dwordx4 v[32:33], v[34:37], off nt
.LBB0_397:
	s_or_b64 exec, exec, s[86:87]
	v_mov_b32_e32 v32, 0
	v_mov_b32_e32 v34, 0
	v_mov_b32_e32 v35, 0
	v_mov_b32_e32 v36, 0
	v_mov_b32_e32 v37, 0
	s_and_saveexec_b64 s[86:87], s[80:81]
	ds_read_b128 v[34:37], v237 offset:16
	s_or_b64 exec, exec, s[86:87]
	v_mov_b32_e32 v38, v192
	v_mov_b32_e32 v39, v192
	v_pk_mul_f32 v[30:31], v[30:31], v[38:39]
	v_pk_mul_f32 v[28:29], v[28:29], v[192:193]
	s_waitcnt lgkmcnt(0)
	v_mov_b32_dpp v48, v34 row_ror:1 row_mask:0xf bank_mask:0xf bound_ctrl:1
	v_mov_b32_dpp v50, v34 row_ror:2 row_mask:0xf bank_mask:0xf bound_ctrl:1
	v_mov_b32_dpp v49, v35 row_ror:1 row_mask:0xf bank_mask:0xf bound_ctrl:1
	v_mov_b32_dpp v51, v35 row_ror:2 row_mask:0xf bank_mask:0xf bound_ctrl:1
	v_mov_b32_dpp v52, v36 row_ror:1 row_mask:0xf bank_mask:0xf bound_ctrl:1
	v_mov_b32_dpp v36, v36 row_ror:2 row_mask:0xf bank_mask:0xf bound_ctrl:1
	v_mov_b32_dpp v53, v37 row_ror:1 row_mask:0xf bank_mask:0xf bound_ctrl:1
	v_mov_b32_dpp v37, v37 row_ror:2 row_mask:0xf bank_mask:0xf bound_ctrl:1
	v_mov_b32_dpp v48, v28 row_shr:1 row_mask:0xf bank_mask:0xf
	v_mov_b32_dpp v50, v28 row_shr:2 row_mask:0xf bank_mask:0xf
	v_mov_b32_dpp v49, v29 row_shr:1 row_mask:0xf bank_mask:0xf
	v_mov_b32_dpp v51, v29 row_shr:2 row_mask:0xf bank_mask:0xf
	v_mov_b32_dpp v52, v30 row_shr:1 row_mask:0xf bank_mask:0xf
	v_mov_b32_dpp v36, v30 row_shr:2 row_mask:0xf bank_mask:0xf
	v_mov_b32_dpp v53, v31 row_shr:1 row_mask:0xf bank_mask:0xf
	v_mov_b32_dpp v37, v31 row_shr:2 row_mask:0xf bank_mask:0xf
	v_mov_b32_e32 v33, 0
	v_mov_b32_e32 v34, 0
	v_mov_b32_e32 v35, 0
	s_and_saveexec_b64 s[86:87], s[80:81]
	ds_read_b128 v[32:35], v237 offset:528
	s_or_b64 exec, exec, s[86:87]
	v_pk_fma_f32 v[36:37], v[94:95], v[36:37], v[130:131]
	v_pk_mul_f32 v[26:27], v[26:27], v[38:39]
	v_pk_fma_f32 v[36:37], v[118:119], v[52:53], v[36:37]
	v_pk_mul_f32 v[24:25], v[24:25], v[192:193]
	v_pk_fma_f32 v[36:37], v[30:31], v[122:123], v[36:37]
	s_waitcnt lgkmcnt(0)
; #define PG8_LAS __attribute__((address_space(3)))
;     __device__ __forceinline__ void operator()(f32x4 (&acc)[2][2][4][2], const Unit& u, int wr, int wc, int fr, int fq, PG8_LAS unsigned char* lds, int wid, int lane) const {
;     ...
;         for (int n = 0; n < 2; ++n) {
;             f32x4 w[2][3], bs[2];
; #pragma unroll
;             for (int bj = 0; bj < 2; ++bj) {
; #pragma unroll
;                 for (int k = 0; k < 3; ++k) w[bj][k] = *(const f32x4*)(cw + k * 11008 + bj * 5504 + j0 + 4 * n);
;                 bs[bj] = *(const f32x4*)(cb + bj * 5504 + j0 + 4 * n); }
; #pragma unroll
;             for (int ai = 0; ai < 2; ++ai) { const int b = 2 * ai + wr;
; #pragma unroll
;                 for (int m = 0; m < 4; ++m) { f32x4 c[2];
; #pragma unroll
;                     for (int bj = 0; bj < 2; ++bj) { const f32x4 cur = acc[ai][bj][m][n]; f32x4 prev;
;                         if (m > 0) prev = acc[ai][bj][m > 0 ? m - 1 : 0][n];
;                         else { prev = (f32x4){0.f, 0.f, 0.f, 0.f}; if (b > 0 && fr >= 14) prev = *(const PG8_LAS f32x4*)(X + ((b - 1) * 2 + fr - 14) * 256 + bj * HALF + wc * 32 + 8 * fq + 4 * n); }
;                         f32x4 p1, p2;
; #pragma unroll
;                         for (int j = 0; j < 4; ++j) { const float r1 = PG8_ROR(prev[j], 0x121), r2 = PG8_ROR(prev[j], 0x122);
;                             p1[j] = PG8_DPP(r1, cur[j], 0x111); p2[j] = PG8_DPP(r2, cur[j], 0x112); }
;                         c[bj] = bs[bj] + w[bj][0] * p2 + w[bj][1] * p1 + w[bj][2] * cur; }
;                     float h4[4];
; #pragma unroll
;                     for (int j = 0; j < 4; ++j) h4[j] = c[0][j] * __builtin_amdgcn_rcpf(1.0f + __expf(-c[0][j])) * c[1][j];
;                     if (n == 0) { pk0[ai][m][0] = cvt_pk_bf16(h4[0], h4[1]); pk0[ai][m][1] = cvt_pk_bf16(h4[2], h4[3]); }
;                     else { u32x4 pk; pk.x = pk0[ai][m][0]; pk.y = pk0[ai][m][1]; pk.z = cvt_pk_bf16(h4[0], h4[1]); pk.w = cvt_pk_bf16(h4[2], h4[3]);
;                         *(PG8_LAS u32x4*)(st + fr * 80 + fq * 16) = pk;
;                         const u32x4 x = *(const PG8_LAS u32x4*)(st + (lane >> 2) * 80 + (lane & 3) * 16);
;                         const int t2 = ai * HALF + wr * 64 + m * 16 + (lane >> 2), gr = grow0 + t2;
;                         if (t2 >= 2 && gr < 8192) *(u32x4*)(HM + (size_t)gr * 5504 + u.pn * 128 + wc * 32 + 8 * (lane & 3)) = x; } } }
	v_mov_b32_dpp v38, v32 row_ror:1 row_mask:0xf bank_mask:0xf bound_ctrl:1
	v_mul_f32_e32 v52, 0xbfb8aa3b, v37
	v_exp_f32_e32 v52, v52
	v_mov_b32_dpp v32, v32 row_ror:2 row_mask:0xf bank_mask:0xf bound_ctrl:1
	v_mov_b32_dpp v39, v33 row_ror:1 row_mask:0xf bank_mask:0xf bound_ctrl:1
	v_mov_b32_dpp v33, v33 row_ror:2 row_mask:0xf bank_mask:0xf bound_ctrl:1
	v_mov_b32_dpp v32, v24 row_shr:2 row_mask:0xf bank_mask:0xf
	v_mov_b32_dpp v38, v24 row_shr:1 row_mask:0xf bank_mask:0xf
	v_mov_b32_dpp v33, v25 row_shr:2 row_mask:0xf bank_mask:0xf
	v_mov_b32_dpp v39, v25 row_shr:1 row_mask:0xf bank_mask:0xf
	v_pk_fma_f32 v[32:33], v[106:107], v[32:33], v[124:125]
	v_pk_fma_f32 v[50:51], v[92:93], v[50:51], v[128:129]
	v_pk_fma_f32 v[32:33], v[84:85], v[38:39], v[32:33]
	v_add_f32_e32 v38, 1.0, v52
	v_pk_fma_f32 v[48:49], v[116:117], v[48:49], v[50:51]
	v_mov_b32_dpp v50, v34 row_ror:1 row_mask:0xf bank_mask:0xf bound_ctrl:1
	v_mov_b32_dpp v34, v34 row_ror:2 row_mask:0xf bank_mask:0xf bound_ctrl:1
	v_mov_b32_dpp v51, v35 row_ror:1 row_mask:0xf bank_mask:0xf bound_ctrl:1
	v_mov_b32_dpp v35, v35 row_ror:2 row_mask:0xf bank_mask:0xf bound_ctrl:1
	v_rcp_f32_e32 v38, v38
	v_mul_f32_e32 v39, 0xbfb8aa3b, v36
	v_mov_b32_dpp v34, v26 row_shr:2 row_mask:0xf bank_mask:0xf
	v_mov_b32_dpp v35, v27 row_shr:2 row_mask:0xf bank_mask:0xf
	v_exp_f32_e32 v39, v39
	v_mov_b32_dpp v50, v26 row_shr:1 row_mask:0xf bank_mask:0xf
	v_mov_b32_dpp v51, v27 row_shr:1 row_mask:0xf bank_mask:0xf
	v_pk_fma_f32 v[34:35], v[108:109], v[34:35], v[126:127]
	v_pk_fma_f32 v[48:49], v[28:29], v[120:121], v[48:49]
	v_pk_fma_f32 v[34:35], v[86:87], v[50:51], v[34:35]
	v_mul_f32_e32 v37, v37, v38
	v_pk_fma_f32 v[34:35], v[26:27], v[90:91], v[34:35]
	v_mul_f32_e32 v38, 0xbfb8aa3b, v49
	v_mul_f32_e32 v35, v37, v35
	v_add_f32_e32 v37, 1.0, v39
	v_rcp_f32_e32 v37, v37
	v_exp_f32_e32 v38, v38
	v_mul_f32_e32 v39, 0xbfb8aa3b, v48
	v_exp_f32_e32 v39, v39
	v_mul_f32_e32 v36, v36, v37
	v_add_f32_e32 v37, 1.0, v38
	v_rcp_f32_e32 v37, v37
	v_add_f32_e32 v38, 1.0, v39
	v_rcp_f32_e32 v38, v38
	v_pk_fma_f32 v[32:33], v[24:25], v[88:89], v[32:33]
	v_mul_f32_e32 v34, v36, v34
	v_mul_f32_e32 v36, v49, v37
	v_mul_f32_e32 v33, v36, v33
	v_mul_f32_e32 v36, v48, v38
	v_mul_f32_e32 v32, v36, v32
	v_cvt_pk_bf16_f32 v82, v32, v33
	v_add_u32_e32 v32, 0x80, v235
	v_add_u32_e32 v32, s72, v32
	v_cmp_gt_i32_e32 vcc, s37, v32
	s_and_b64 s[88:89], s[44:45], vcc
	v_cvt_pk_bf16_f32 v83, v34, v35
	ds_write_b128 v240, v[80:83]
	s_and_saveexec_b64 s[86:87], s[88:89]
	s_cbranch_execz .LBB0_403
	ds_read_b128 v[34:37], v241
	v_mov_b64_e32 v[38:39], s[12:13]
	s_movk_i32 s20, 0x2b00
	v_mad_i64_i32 v[32:33], s[88:89], v32, s20, v[38:39]
	v_lshl_add_u64 v[32:33], s[0:1], 1, v[32:33]
	s_lshl_b32 s20, s97, 1
	v_lshl_add_u64 v[32:33], v[32:33], 0, s[20:21]
	v_lshl_add_u64 v[32:33], v[32:33], 0, v[0:1]
	s_waitcnt lgkmcnt(0)
	global_store_dwordx4 v[32:33], v[34:37], off nt
.LBB0_403:
	s_or_b64 exec, exec, s[86:87]
	v_mov_b32_e32 v191, v190
	v_mov_b32_e32 v32, v190
	v_mov_b32_e32 v33, v190
	v_pk_mul_f32 v[22:23], v[22:23], v[32:33]
	v_pk_mul_f32 v[20:21], v[20:21], v[190:191]
	v_pk_mul_f32 v[18:19], v[18:19], v[32:33]
	v_mov_b32_dpp v32, v28 row_ror:1 row_mask:0xf bank_mask:0xf bound_ctrl:1
	v_mov_b32_dpp v28, v28 row_ror:2 row_mask:0xf bank_mask:0xf bound_ctrl:1
	v_mov_b32_dpp v33, v29 row_ror:1 row_mask:0xf bank_mask:0xf bound_ctrl:1
	v_mov_b32_dpp v29, v29 row_ror:2 row_mask:0xf bank_mask:0xf bound_ctrl:1
	v_mov_b32_dpp v28, v20 row_shr:2 row_mask:0xf bank_mask:0xf
	v_mov_b32_dpp v34, v30 row_ror:1 row_mask:0xf bank_mask:0xf bound_ctrl:1
	v_mov_b32_dpp v29, v21 row_shr:2 row_mask:0xf bank_mask:0xf
	v_mov_b32_dpp v30, v30 row_ror:2 row_mask:0xf bank_mask:0xf bound_ctrl:1
	v_mov_b32_dpp v35, v31 row_ror:1 row_mask:0xf bank_mask:0xf bound_ctrl:1
	v_mov_b32_dpp v31, v31 row_ror:2 row_mask:0xf bank_mask:0xf bound_ctrl:1
	v_mov_b32_dpp v32, v20 row_shr:1 row_mask:0xf bank_mask:0xf
	v_mov_b32_dpp v33, v21 row_shr:1 row_mask:0xf bank_mask:0xf
	v_mov_b32_dpp v30, v22 row_shr:2 row_mask:0xf bank_mask:0xf
	v_mov_b32_dpp v31, v23 row_shr:2 row_mask:0xf bank_mask:0xf
	v_pk_fma_f32 v[28:29], v[92:93], v[28:29], v[128:129]
	v_pk_mul_f32 v[16:17], v[16:17], v[190:191]
	v_mov_b32_dpp v34, v22 row_shr:1 row_mask:0xf bank_mask:0xf
	v_mov_b32_dpp v35, v23 row_shr:1 row_mask:0xf bank_mask:0xf
	v_pk_fma_f32 v[30:31], v[94:95], v[30:31], v[130:131]
	v_pk_fma_f32 v[28:29], v[116:117], v[32:33], v[28:29]
	v_mov_b32_dpp v32, v24 row_ror:1 row_mask:0xf bank_mask:0xf bound_ctrl:1
	v_mov_b32_dpp v24, v24 row_ror:2 row_mask:0xf bank_mask:0xf bound_ctrl:1
	v_mov_b32_dpp v33, v25 row_ror:1 row_mask:0xf bank_mask:0xf bound_ctrl:1
	v_mov_b32_dpp v25, v25 row_ror:2 row_mask:0xf bank_mask:0xf bound_ctrl:1
	v_pk_fma_f32 v[30:31], v[118:119], v[34:35], v[30:31]
	v_mov_b32_dpp v24, v16 row_shr:2 row_mask:0xf bank_mask:0xf
	v_mov_b32_dpp v25, v17 row_shr:2 row_mask:0xf bank_mask:0xf
	v_pk_fma_f32 v[30:31], v[22:23], v[122:123], v[30:31]
	v_mov_b32_dpp v32, v16 row_shr:1 row_mask:0xf bank_mask:0xf
	v_mov_b32_dpp v33, v17 row_shr:1 row_mask:0xf bank_mask:0xf
	v_pk_fma_f32 v[24:25], v[106:107], v[24:25], v[124:125]
	v_mov_b32_dpp v34, v26 row_ror:1 row_mask:0xf bank_mask:0xf bound_ctrl:1
	v_pk_fma_f32 v[24:25], v[84:85], v[32:33], v[24:25]
	v_mul_f32_e32 v32, 0xbfb8aa3b, v31
	v_exp_f32_e32 v32, v32
	v_mov_b32_dpp v26, v26 row_ror:2 row_mask:0xf bank_mask:0xf bound_ctrl:1
	v_mov_b32_dpp v35, v27 row_ror:1 row_mask:0xf bank_mask:0xf bound_ctrl:1
	v_mov_b32_dpp v27, v27 row_ror:2 row_mask:0xf bank_mask:0xf bound_ctrl:1
	v_add_f32_e32 v32, 1.0, v32
	v_rcp_f32_e32 v32, v32
; #define PG8_LAS __attribute__((address_space(3)))
;     __device__ __forceinline__ void operator()(f32x4 (&acc)[2][2][4][2], const Unit& u, int wr, int wc, int fr, int fq, PG8_LAS unsigned char* lds, int wid, int lane) const {
;     ...
;         for (int n = 0; n < 2; ++n) {
;             f32x4 w[2][3], bs[2];
; #pragma unroll
;             for (int bj = 0; bj < 2; ++bj) {
; #pragma unroll
;                 for (int k = 0; k < 3; ++k) w[bj][k] = *(const f32x4*)(cw + k * 11008 + bj * 5504 + j0 + 4 * n);
;                 bs[bj] = *(const f32x4*)(cb + bj * 5504 + j0 + 4 * n); }
; #pragma unroll
;             for (int ai = 0; ai < 2; ++ai) { const int b = 2 * ai + wr;
; #pragma unroll
;                 for (int m = 0; m < 4; ++m) { f32x4 c[2];
; #pragma unroll
;                     for (int bj = 0; bj < 2; ++bj) { const f32x4 cur = acc[ai][bj][m][n]; f32x4 prev;
;                         if (m > 0) prev = acc[ai][bj][m > 0 ? m - 1 : 0][n];
;                         else { prev = (f32x4){0.f, 0.f, 0.f, 0.f}; if (b > 0 && fr >= 14) prev = *(const PG8_LAS f32x4*)(X + ((b - 1) * 2 + fr - 14) * 256 + bj * HALF + wc * 32 + 8 * fq + 4 * n); }
;                         f32x4 p1, p2;
; #pragma unroll
;                         for (int j = 0; j < 4; ++j) { const float r1 = PG8_ROR(prev[j], 0x121), r2 = PG8_ROR(prev[j], 0x122);
;                             p1[j] = PG8_DPP(r1, cur[j], 0x111); p2[j] = PG8_DPP(r2, cur[j], 0x112); }
;                         c[bj] = bs[bj] + w[bj][0] * p2 + w[bj][1] * p1 + w[bj][2] * cur; }
;                     float h4[4];
; #pragma unroll
;                     for (int j = 0; j < 4; ++j) h4[j] = c[0][j] * __builtin_amdgcn_rcpf(1.0f + __expf(-c[0][j])) * c[1][j];
;                     if (n == 0) { pk0[ai][m][0] = cvt_pk_bf16(h4[0], h4[1]); pk0[ai][m][1] = cvt_pk_bf16(h4[2], h4[3]); }
;                     else { u32x4 pk; pk.x = pk0[ai][m][0]; pk.y = pk0[ai][m][1]; pk.z = cvt_pk_bf16(h4[0], h4[1]); pk.w = cvt_pk_bf16(h4[2], h4[3]);
;                         *(PG8_LAS u32x4*)(st + fr * 80 + fq * 16) = pk;
;                         const u32x4 x = *(const PG8_LAS u32x4*)(st + (lane >> 2) * 80 + (lane & 3) * 16);
;                         const int t2 = ai * HALF + wr * 64 + m * 16 + (lane >> 2), gr = grow0 + t2;
;                         if (t2 >= 2 && gr < 8192) *(u32x4*)(HM + (size_t)gr * 5504 + u.pn * 128 + wc * 32 + 8 * (lane & 3)) = x; } } }
	v_mov_b32_dpp v26, v18 row_shr:2 row_mask:0xf bank_mask:0xf
	v_mov_b32_dpp v27, v19 row_shr:2 row_mask:0xf bank_mask:0xf
	v_mov_b32_dpp v34, v18 row_shr:1 row_mask:0xf bank_mask:0xf
	v_mov_b32_dpp v35, v19 row_shr:1 row_mask:0xf bank_mask:0xf
	v_pk_fma_f32 v[26:27], v[108:109], v[26:27], v[126:127]
	v_mul_f32_e32 v31, v31, v32
	v_pk_fma_f32 v[26:27], v[86:87], v[34:35], v[26:27]
	v_pk_fma_f32 v[28:29], v[20:21], v[120:121], v[28:29]
	v_pk_fma_f32 v[26:27], v[18:19], v[90:91], v[26:27]
	v_pk_fma_f32 v[24:25], v[16:17], v[88:89], v[24:25]
	v_mul_f32_e32 v27, v31, v27
	v_mul_f32_e32 v31, 0xbfb8aa3b, v30
	v_exp_f32_e32 v31, v31
	s_nop 0
	v_add_f32_e32 v31, 1.0, v31
	v_rcp_f32_e32 v31, v31
	s_nop 0
	v_mul_f32_e32 v30, v30, v31
	v_mul_f32_e32 v26, v30, v26
	v_mul_f32_e32 v30, 0xbfb8aa3b, v29
	v_exp_f32_e32 v30, v30
	s_nop 0
	v_add_f32_e32 v30, 1.0, v30
	v_rcp_f32_e32 v30, v30
	s_nop 0
	v_mul_f32_e32 v29, v29, v30
	v_mul_f32_e32 v25, v29, v25
	v_mul_f32_e32 v29, 0xbfb8aa3b, v28
	v_exp_f32_e32 v29, v29
	s_nop 0
	v_add_f32_e32 v29, 1.0, v29
	v_rcp_f32_e32 v29, v29
	s_nop 0
	v_mul_f32_e32 v28, v28, v29
	v_mul_f32_e32 v24, v28, v24
	v_cvt_pk_bf16_f32 v80, v24, v25
	v_add_u32_e32 v24, 0x90, v235
	v_add_u32_e32 v24, s72, v24
	v_cmp_gt_i32_e32 vcc, s37, v24
	s_and_b64 s[88:89], s[46:47], vcc
	v_cvt_pk_bf16_f32 v81, v26, v27
	ds_write_b128 v240, v[78:81]
	s_and_saveexec_b64 s[86:87], s[88:89]
	s_cbranch_execz .LBB0_405
	ds_read_b128 v[26:29], v241
	v_mov_b64_e32 v[30:31], s[12:13]
	s_movk_i32 s20, 0x2b00
	v_mad_i64_i32 v[24:25], s[88:89], v24, s20, v[30:31]
	v_lshl_add_u64 v[24:25], s[0:1], 1, v[24:25]
	s_lshl_b32 s20, s97, 1
	v_lshl_add_u64 v[24:25], v[24:25], 0, s[20:21]
	v_lshl_add_u64 v[24:25], v[24:25], 0, v[0:1]
	s_waitcnt lgkmcnt(0)
	global_store_dwordx4 v[24:25], v[26:29], off nt
.LBB0_405:
	s_or_b64 exec, exec, s[86:87]
	v_mov_b32_e32 v189, v188
	v_mov_b32_e32 v24, v188
	v_mov_b32_e32 v25, v188
	v_pk_mul_f32 v[14:15], v[14:15], v[24:25]
	v_pk_mul_f32 v[12:13], v[12:13], v[188:189]
	v_pk_mul_f32 v[10:11], v[10:11], v[24:25]
	v_mov_b32_dpp v24, v20 row_ror:1 row_mask:0xf bank_mask:0xf bound_ctrl:1
	v_mov_b32_dpp v20, v20 row_ror:2 row_mask:0xf bank_mask:0xf bound_ctrl:1
	v_mov_b32_dpp v25, v21 row_ror:1 row_mask:0xf bank_mask:0xf bound_ctrl:1
	v_mov_b32_dpp v21, v21 row_ror:2 row_mask:0xf bank_mask:0xf bound_ctrl:1
	v_mov_b32_dpp v20, v12 row_shr:2 row_mask:0xf bank_mask:0xf
	v_mov_b32_dpp v26, v22 row_ror:1 row_mask:0xf bank_mask:0xf bound_ctrl:1
	v_mov_b32_dpp v21, v13 row_shr:2 row_mask:0xf bank_mask:0xf
	v_mov_b32_dpp v22, v22 row_ror:2 row_mask:0xf bank_mask:0xf bound_ctrl:1
	v_mov_b32_dpp v27, v23 row_ror:1 row_mask:0xf bank_mask:0xf bound_ctrl:1
	v_mov_b32_dpp v23, v23 row_ror:2 row_mask:0xf bank_mask:0xf bound_ctrl:1
	v_mov_b32_dpp v24, v12 row_shr:1 row_mask:0xf bank_mask:0xf
	v_mov_b32_dpp v25, v13 row_shr:1 row_mask:0xf bank_mask:0xf
	v_mov_b32_dpp v22, v14 row_shr:2 row_mask:0xf bank_mask:0xf
	v_mov_b32_dpp v23, v15 row_shr:2 row_mask:0xf bank_mask:0xf
	v_pk_fma_f32 v[20:21], v[92:93], v[20:21], v[128:129]
	v_pk_mul_f32 v[8:9], v[8:9], v[188:189]
	v_mov_b32_dpp v26, v14 row_shr:1 row_mask:0xf bank_mask:0xf
	v_mov_b32_dpp v27, v15 row_shr:1 row_mask:0xf bank_mask:0xf
	v_pk_fma_f32 v[22:23], v[94:95], v[22:23], v[130:131]
	v_pk_fma_f32 v[20:21], v[116:117], v[24:25], v[20:21]
	v_mov_b32_dpp v24, v16 row_ror:1 row_mask:0xf bank_mask:0xf bound_ctrl:1
	v_mov_b32_dpp v16, v16 row_ror:2 row_mask:0xf bank_mask:0xf bound_ctrl:1
	v_mov_b32_dpp v25, v17 row_ror:1 row_mask:0xf bank_mask:0xf bound_ctrl:1
	v_mov_b32_dpp v17, v17 row_ror:2 row_mask:0xf bank_mask:0xf bound_ctrl:1
	v_pk_fma_f32 v[22:23], v[118:119], v[26:27], v[22:23]
	v_mov_b32_dpp v16, v8 row_shr:2 row_mask:0xf bank_mask:0xf
	v_mov_b32_dpp v17, v9 row_shr:2 row_mask:0xf bank_mask:0xf
	v_pk_fma_f32 v[22:23], v[14:15], v[122:123], v[22:23]
	v_mov_b32_dpp v24, v8 row_shr:1 row_mask:0xf bank_mask:0xf
	v_mov_b32_dpp v25, v9 row_shr:1 row_mask:0xf bank_mask:0xf
	v_pk_fma_f32 v[16:17], v[106:107], v[16:17], v[124:125]
	v_mov_b32_dpp v26, v18 row_ror:1 row_mask:0xf bank_mask:0xf bound_ctrl:1
	v_pk_fma_f32 v[16:17], v[84:85], v[24:25], v[16:17]
	v_mul_f32_e32 v24, 0xbfb8aa3b, v23
	v_exp_f32_e32 v24, v24
	v_mov_b32_dpp v18, v18 row_ror:2 row_mask:0xf bank_mask:0xf bound_ctrl:1
	v_mov_b32_dpp v27, v19 row_ror:1 row_mask:0xf bank_mask:0xf bound_ctrl:1
	v_mov_b32_dpp v19, v19 row_ror:2 row_mask:0xf bank_mask:0xf bound_ctrl:1
	v_add_f32_e32 v24, 1.0, v24
	v_rcp_f32_e32 v24, v24
	v_mov_b32_dpp v18, v10 row_shr:2 row_mask:0xf bank_mask:0xf
	v_mov_b32_dpp v19, v11 row_shr:2 row_mask:0xf bank_mask:0xf
	v_mov_b32_dpp v26, v10 row_shr:1 row_mask:0xf bank_mask:0xf
	v_mov_b32_dpp v27, v11 row_shr:1 row_mask:0xf bank_mask:0xf
	v_pk_fma_f32 v[18:19], v[108:109], v[18:19], v[126:127]
	v_mul_f32_e32 v23, v23, v24
	v_pk_fma_f32 v[18:19], v[86:87], v[26:27], v[18:19]
	v_pk_fma_f32 v[20:21], v[12:13], v[120:121], v[20:21]
	v_pk_fma_f32 v[18:19], v[10:11], v[90:91], v[18:19]
	v_pk_fma_f32 v[16:17], v[8:9], v[88:89], v[16:17]
	v_mul_f32_e32 v19, v23, v19
	v_mul_f32_e32 v23, 0xbfb8aa3b, v22
	v_exp_f32_e32 v23, v23
	s_nop 0
	v_add_f32_e32 v23, 1.0, v23
	v_rcp_f32_e32 v23, v23
	s_nop 0
	v_mul_f32_e32 v22, v22, v23
	v_mul_f32_e32 v18, v22, v18
	v_mul_f32_e32 v22, 0xbfb8aa3b, v21
	v_exp_f32_e32 v22, v22
	s_nop 0
	v_add_f32_e32 v22, 1.0, v22
	v_rcp_f32_e32 v22, v22
	s_nop 0
	v_mul_f32_e32 v21, v21, v22
	v_mul_f32_e32 v17, v21, v17
	v_mul_f32_e32 v21, 0xbfb8aa3b, v20
	v_exp_f32_e32 v21, v21
	s_nop 0
	v_add_f32_e32 v21, 1.0, v21
	v_rcp_f32_e32 v21, v21
	s_nop 0
	v_mul_f32_e32 v20, v20, v21
	v_mul_f32_e32 v16, v20, v16
	v_cvt_pk_bf16_f32 v74, v16, v17
	v_add_u32_e32 v16, 0xa0, v235
	v_add_u32_e32 v16, s72, v16
	v_cmp_gt_i32_e32 vcc, s37, v16
	s_and_b64 s[88:89], s[4:5], vcc
	v_cvt_pk_bf16_f32 v75, v18, v19
	ds_write_b128 v240, v[72:75]
	s_and_saveexec_b64 s[86:87], s[88:89]
	s_cbranch_execz .LBB0_407
	ds_read_b128 v[18:21], v241
	v_mov_b64_e32 v[22:23], s[12:13]
	s_movk_i32 s20, 0x2b00
	v_mad_i64_i32 v[16:17], s[88:89], v16, s20, v[22:23]
	v_lshl_add_u64 v[16:17], s[0:1], 1, v[16:17]
	s_lshl_b32 s20, s97, 1
	v_lshl_add_u64 v[16:17], v[16:17], 0, s[20:21]
	v_lshl_add_u64 v[16:17], v[16:17], 0, v[0:1]
	s_waitcnt lgkmcnt(0)
	global_store_dwordx4 v[16:17], v[18:21], off nt
; #define PG8_LAS __attribute__((address_space(3)))
;     __device__ __forceinline__ void operator()(f32x4 (&acc)[2][2][4][2], const Unit& u, int wr, int wc, int fr, int fq, PG8_LAS unsigned char* lds, int wid, int lane) const {
;     ...
;         for (int n = 0; n < 2; ++n) {
;             f32x4 w[2][3], bs[2];
; #pragma unroll
;             for (int bj = 0; bj < 2; ++bj) {
; #pragma unroll
;                 for (int k = 0; k < 3; ++k) w[bj][k] = *(const f32x4*)(cw + k * 11008 + bj * 5504 + j0 + 4 * n);
;                 bs[bj] = *(const f32x4*)(cb + bj * 5504 + j0 + 4 * n); }
; #pragma unroll
;             for (int ai = 0; ai < 2; ++ai) { const int b = 2 * ai + wr;
; #pragma unroll
;                 for (int m = 0; m < 4; ++m) { f32x4 c[2];
; #pragma unroll
;                     for (int bj = 0; bj < 2; ++bj) { const f32x4 cur = acc[ai][bj][m][n]; f32x4 prev;
;                         if (m > 0) prev = acc[ai][bj][m > 0 ? m - 1 : 0][n];
;                         else { prev = (f32x4){0.f, 0.f, 0.f, 0.f}; if (b > 0 && fr >= 14) prev = *(const PG8_LAS f32x4*)(X + ((b - 1) * 2 + fr - 14) * 256 + bj * HALF + wc * 32 + 8 * fq + 4 * n); }
;                         f32x4 p1, p2;
; #pragma unroll
;                         for (int j = 0; j < 4; ++j) { const float r1 = PG8_ROR(prev[j], 0x121), r2 = PG8_ROR(prev[j], 0x122);
;                             p1[j] = PG8_DPP(r1, cur[j], 0x111); p2[j] = PG8_DPP(r2, cur[j], 0x112); }
;                         c[bj] = bs[bj] + w[bj][0] * p2 + w[bj][1] * p1 + w[bj][2] * cur; }
;                     float h4[4];
; #pragma unroll
;                     for (int j = 0; j < 4; ++j) h4[j] = c[0][j] * __builtin_amdgcn_rcpf(1.0f + __expf(-c[0][j])) * c[1][j];
;                     if (n == 0) { pk0[ai][m][0] = cvt_pk_bf16(h4[0], h4[1]); pk0[ai][m][1] = cvt_pk_bf16(h4[2], h4[3]); }
;                     else { u32x4 pk; pk.x = pk0[ai][m][0]; pk.y = pk0[ai][m][1]; pk.z = cvt_pk_bf16(h4[0], h4[1]); pk.w = cvt_pk_bf16(h4[2], h4[3]);
;                         *(PG8_LAS u32x4*)(st + fr * 80 + fq * 16) = pk;
;                         const u32x4 x = *(const PG8_LAS u32x4*)(st + (lane >> 2) * 80 + (lane & 3) * 16);
;                         const int t2 = ai * HALF + wr * 64 + m * 16 + (lane >> 2), gr = grow0 + t2;
;                         if (t2 >= 2 && gr < 8192) *(u32x4*)(HM + (size_t)gr * 5504 + u.pn * 128 + wc * 32 + 8 * (lane & 3)) = x; } } }
.LBB0_407:
	s_or_b64 exec, exec, s[86:87]
	s_nop 0
	v_mov_b32_dpp v18, v14 row_ror:1 row_mask:0xf bank_mask:0xf bound_ctrl:1
	v_mov_b32_dpp v14, v14 row_ror:2 row_mask:0xf bank_mask:0xf bound_ctrl:1
	v_mov_b32_dpp v19, v15 row_ror:1 row_mask:0xf bank_mask:0xf bound_ctrl:1
	v_mov_b32_dpp v15, v15 row_ror:2 row_mask:0xf bank_mask:0xf bound_ctrl:1
	v_mov_b32_dpp v14, v46 row_shr:2 row_mask:0xf bank_mask:0xf
	v_mov_b32_dpp v18, v46 row_shr:1 row_mask:0xf bank_mask:0xf
	v_mov_b32_dpp v15, v47 row_shr:2 row_mask:0xf bank_mask:0xf
	v_mov_b32_dpp v19, v47 row_shr:1 row_mask:0xf bank_mask:0xf
	v_pk_fma_f32 v[14:15], v[94:95], v[14:15], v[130:131]
	v_mov_b32_dpp v16, v12 row_ror:1 row_mask:0xf bank_mask:0xf bound_ctrl:1
	v_pk_fma_f32 v[14:15], v[118:119], v[18:19], v[14:15]
	v_mov_b32_dpp v12, v12 row_ror:2 row_mask:0xf bank_mask:0xf bound_ctrl:1
	v_mov_b32_dpp v17, v13 row_ror:1 row_mask:0xf bank_mask:0xf bound_ctrl:1
	v_mov_b32_dpp v13, v13 row_ror:2 row_mask:0xf bank_mask:0xf bound_ctrl:1
	v_pk_fma_f32 v[14:15], v[46:47], v[122:123], v[14:15]
	v_mov_b32_dpp v12, v44 row_shr:2 row_mask:0xf bank_mask:0xf
	v_mov_b32_dpp v13, v45 row_shr:2 row_mask:0xf bank_mask:0xf
	v_mul_f32_e32 v20, 0xbfb8aa3b, v15
	v_mov_b32_dpp v16, v44 row_shr:1 row_mask:0xf bank_mask:0xf
	v_mov_b32_dpp v17, v45 row_shr:1 row_mask:0xf bank_mask:0xf
	v_pk_fma_f32 v[12:13], v[92:93], v[12:13], v[128:129]
	v_exp_f32_e32 v20, v20
	v_pk_fma_f32 v[12:13], v[116:117], v[16:17], v[12:13]
	v_mov_b32_dpp v16, v8 row_ror:1 row_mask:0xf bank_mask:0xf bound_ctrl:1
	v_mov_b32_dpp v8, v8 row_ror:2 row_mask:0xf bank_mask:0xf bound_ctrl:1
	v_mov_b32_dpp v17, v9 row_ror:1 row_mask:0xf bank_mask:0xf bound_ctrl:1
	v_mov_b32_dpp v9, v9 row_ror:2 row_mask:0xf bank_mask:0xf bound_ctrl:1
	v_mov_b32_dpp v8, v40 row_shr:2 row_mask:0xf bank_mask:0xf
	v_mov_b32_dpp v16, v40 row_shr:1 row_mask:0xf bank_mask:0xf
	v_mov_b32_dpp v9, v41 row_shr:2 row_mask:0xf bank_mask:0xf
	v_mov_b32_dpp v17, v41 row_shr:1 row_mask:0xf bank_mask:0xf
	v_pk_fma_f32 v[8:9], v[106:107], v[8:9], v[124:125]
	v_mov_b32_dpp v18, v10 row_ror:1 row_mask:0xf bank_mask:0xf bound_ctrl:1
	v_pk_fma_f32 v[8:9], v[84:85], v[16:17], v[8:9]
	v_add_f32_e32 v16, 1.0, v20
	v_mov_b32_dpp v10, v10 row_ror:2 row_mask:0xf bank_mask:0xf bound_ctrl:1
	v_mov_b32_dpp v19, v11 row_ror:1 row_mask:0xf bank_mask:0xf bound_ctrl:1
	v_mov_b32_dpp v11, v11 row_ror:2 row_mask:0xf bank_mask:0xf bound_ctrl:1
	v_rcp_f32_e32 v16, v16
	v_mul_f32_e32 v17, 0xbfb8aa3b, v14
	v_mov_b32_dpp v10, v42 row_shr:2 row_mask:0xf bank_mask:0xf
	v_mov_b32_dpp v11, v43 row_shr:2 row_mask:0xf bank_mask:0xf
	v_exp_f32_e32 v17, v17
	v_mov_b32_dpp v18, v42 row_shr:1 row_mask:0xf bank_mask:0xf
	v_mov_b32_dpp v19, v43 row_shr:1 row_mask:0xf bank_mask:0xf
	v_pk_fma_f32 v[10:11], v[108:109], v[10:11], v[126:127]
	v_pk_fma_f32 v[12:13], v[44:45], v[120:121], v[12:13]
	v_pk_fma_f32 v[10:11], v[86:87], v[18:19], v[10:11]
	v_mul_f32_e32 v15, v15, v16
	v_pk_fma_f32 v[10:11], v[42:43], v[90:91], v[10:11]
	v_mul_f32_e32 v16, 0xbfb8aa3b, v13
	v_mul_f32_e32 v11, v15, v11
	v_add_f32_e32 v15, 1.0, v17
	v_mul_f32_e32 v17, 0xbfb8aa3b, v12
	v_rcp_f32_e32 v15, v15
	v_exp_f32_e32 v16, v16
	v_exp_f32_e32 v17, v17
	v_pk_fma_f32 v[8:9], v[40:41], v[88:89], v[8:9]
	v_mul_f32_e32 v14, v14, v15
	v_add_f32_e32 v15, 1.0, v16
	v_add_f32_e32 v16, 1.0, v17
	v_rcp_f32_e32 v16, v16
	v_rcp_f32_e32 v15, v15
	v_mul_f32_e32 v10, v14, v10
	v_mul_f32_e32 v12, v12, v16
	v_mul_f32_e32 v13, v13, v15
	v_mul_f32_e32 v8, v12, v8
	v_mul_f32_e32 v9, v13, v9
	v_cvt_pk_bf16_f32 v78, v8, v9
	v_add_u32_e32 v8, 0xb0, v235
	v_add_u32_e32 v8, s72, v8
	v_cmp_gt_i32_e32 vcc, s37, v8
	s_and_b64 s[72:73], s[6:7], vcc
	v_cvt_pk_bf16_f32 v79, v10, v11
	ds_write_b128 v240, v[76:79]
	s_and_saveexec_b64 s[86:87], s[72:73]
	s_cbranch_execz .LBB0_409
	ds_read_b128 v[10:13], v241
	v_mov_b64_e32 v[14:15], s[12:13]
	s_movk_i32 s20, 0x2b00
	v_mad_i64_i32 v[8:9], s[72:73], v8, s20, v[14:15]
	v_lshl_add_u64 v[8:9], s[0:1], 1, v[8:9]
	s_lshl_b32 s20, s97, 1
	v_lshl_add_u64 v[8:9], v[8:9], 0, s[20:21]
	v_lshl_add_u64 v[8:9], v[8:9], 0, v[0:1]
	s_waitcnt lgkmcnt(0)
	global_store_dwordx4 v[8:9], v[10:13], off nt
